# pooling fast path: counted per-row vmcnt waits in the first pass (compute starts when the first row lands) instead of one vmcnt(0)
# baseline (speedup 1.0000x reference)
; __device__ __forceinline__ unsigned pk2(float lo, float hi) { return pg8::cvt_pk_bf16(lo, hi); }
; __global__ void __launch_bounds__(NTHR, 2) hybrid_fwd(Args args) {
;     ...
;         const int gI = lane >> 4, w = 2 << gI;
;         const int t_b = hb * rpb + wave * rows_per; int nr = rpb - wave * rows_per; if (nr > rows_per) nr = rows_per; if (t_b + nr > T) nr = T - t_b;
;         u32x4 qn[16];
;         if (nr > 0) { const int sp0 = t_b & 2047, c0_ = (sp0 + 1) < w ? (sp0 + 1) : w;
; #pragma unroll
;             for (int j = 0; j < 16; ++j) qn[j] = *(const u32x4*)(UB + (size_t)(j < c0_ ? t_b - j : t_b) * 512 + lane * 8); }
;         for (int i = 0; i < nr; ++i) { const int t = t_b + i;
;             const int sp = t & 2047, cnt = (sp + 1) < w ? (sp + 1) : w;
;             u32x4 qv[16];
; #pragma unroll
;             for (int j = 0; j < 16; ++j) qv[j] = qn[j];
;             if (i + 1 < nr) { const int t1 = t + 1, sp1 = t1 & 2047, c1_ = (sp1 + 1) < w ? (sp1 + 1) : w;
; #pragma unroll
;                 for (int j = 0; j < 16; ++j) qn[j] = *(const u32x4*)(UB + (size_t)(j < c1_ ? t1 - j : t1) * 512 + lane * 8); }
;             float a[8];
; #pragma unroll
;             for (int e = 0; e < 8; ++e) a[e] = 0.f;
;             const u32x4 u0 = qv[0];
; #pragma unroll
;             for (int j = 0; j < 16; ++j) { const float mk = j < cnt ? 1.0f : 0.0f; const u32x4 q = qv[j];
;                 a[0] += mk * bflo(q.x); a[1] += mk * bfhi(q.x); a[2] += mk * bflo(q.y); a[3] += mk * bfhi(q.y); a[4] += mk * bflo(q.z); a[5] += mk * bfhi(q.z); a[6] += mk * bflo(q.w); a[7] += mk * bfhi(q.w); }
;             const float ic = 1.0f / (float)cnt;
;             u32x4 o; o.x = pk2(a[0] * ic - bflo(u0.x), a[1] * ic - bfhi(u0.x)); o.y = pk2(a[2] * ic - bflo(u0.y), a[3] * ic - bfhi(u0.y));
;             o.z = pk2(a[4] * ic - bflo(u0.z), a[5] * ic - bfhi(u0.z)); o.w = pk2(a[6] * ic - bflo(u0.w), a[7] * ic - bfhi(u0.w));
;             *(u32x4*)(AD + (size_t)t * 1024 + lane * 8) = o; }
.Lpool_ld_done:
	v_lshrrev_b32_e32 v137, 4, v212
	v_cmp_lt_u32_e32 vcc, 0, v137
	s_nop 1
	v_cndmask_b32_e64 v134, 0, 1.0, vcc
	v_cmp_lt_u32_e32 vcc, 1, v137
	s_nop 1
	v_cndmask_b32_e64 v135, 0, 1.0, vcc
	v_cmp_lt_u32_e32 vcc, 2, v137
	s_nop 1
	v_cndmask_b32_e64 v136, 0, 1.0, vcc
	v_lshlrev_b32_e64 v137, v137, 2
	s_lshl_b32 s98, s10, 11
	s_add_u32 s26, s8, 0x3c00000
	s_addc_u32 s27, s9, 0
	s_add_u32 s26, s26, s98
	s_addc_u32 s27, s27, 0
	v_lshl_add_u64 v[138:139], s[26:27], 0, v[0:1]
	s_mov_b32 s100, 0xffff0000
	s_mov_b64 s[26:27], 0x1000
	v_mov_b32_e32 v175, 0
	v_mov_b32_e32 v176, 0
	v_mov_b32_e32 v177, 0
	v_mov_b32_e32 v178, 0
	v_mov_b32_e32 v179, 0
	v_mov_b32_e32 v180, 0
	v_mov_b32_e32 v181, 0
	v_mov_b32_e32 v182, 0
	v_mov_b32_e32 v183, 0
	v_mov_b32_e32 v184, 0
	v_mov_b32_e32 v185, 0
	v_mov_b32_e32 v186, 0
	v_mov_b32_e32 v187, 0
	v_mov_b32_e32 v188, 0
	v_mov_b32_e32 v189, 0
	v_mov_b32_e32 v190, 0
	v_mov_b32_e32 v191, 0
	v_mov_b32_e32 v192, 0
	v_mov_b32_e32 v193, 0
	v_mov_b32_e32 v194, 0
	v_mov_b32_e32 v195, 0
	v_mov_b32_e32 v196, 0
	v_mov_b32_e32 v197, 0
	v_mov_b32_e32 v198, 0
	v_mov_b32_e32 v199, 0
	v_mov_b32_e32 v200, 0
	v_mov_b32_e32 v201, 0
	v_mov_b32_e32 v202, 0
	v_mov_b32_e32 v203, 0
	v_mov_b32_e32 v204, 0
	v_mov_b32_e32 v205, 0
	v_mov_b32_e32 v206, 0
	v_mov_b32_e32 v207, 0
	v_mov_b32_e32 v208, 0
	v_mov_b32_e32 v209, 0
	v_mov_b32_e32 v210, 0
	v_mov_b32_e32 v211, 0
	v_mov_b32_e32 v221, 0
	v_mov_b32_e32 v222, 0
	v_mov_b32_e32 v223, 0
	v_mov_b32_e32 v224, 0
	v_mov_b32_e32 v225, 0
	v_mov_b32_e32 v226, 0
	v_mov_b32_e32 v227, 0
	v_mov_b32_e32 v228, 0
	v_mov_b32_e32 v229, 0
	v_mov_b32_e32 v230, 0
	v_mov_b32_e32 v231, 0
	v_mov_b32_e32 v232, 0
	v_mov_b32_e32 v233, 0
	v_mov_b32_e32 v234, 0
	v_mov_b32_e32 v235, 0
	v_mov_b32_e32 v236, 0
	v_mov_b32_e32 v237, 0
	v_mov_b32_e32 v238, 0
	v_mov_b32_e32 v239, 0
	v_mov_b32_e32 v240, 0
	v_mov_b32_e32 v241, 0
	v_mov_b32_e32 v242, 0
	v_mov_b32_e32 v243, 0
	s_waitcnt vmcnt(30)
	v_lshlrev_b32_e32 v0, 16, v8
	v_and_b32_e32 v1, s100, v8
	v_lshlrev_b32_e32 v172, 16, v9
	v_and_b32_e32 v173, s100, v9
	v_add_f32_e32 v214, v0, v175
	v_add_f32_e32 v215, v1, v176
	v_add_f32_e32 v216, v172, v177
	v_add_f32_e32 v217, v173, v178
	v_fma_f32 v244, v134, v179, v214
	v_fma_f32 v245, v134, v180, v215
	v_fma_f32 v246, v134, v181, v216
	v_fma_f32 v247, v134, v182, v217
	v_fma_f32 v249, v135, v187, v244
	v_fma_f32 v250, v135, v188, v245
	v_fma_f32 v251, v135, v189, v246
	v_fma_f32 v252, v135, v190, v247
	s_waitcnt vmcnt(29)
	v_lshlrev_b32_e32 v253, 16, v12
	v_and_b32_e32 v254, s100, v12
	v_lshlrev_b32_e32 v255, 16, v13
	v_and_b32_e32 v179, s100, v13
	v_add_f32_e32 v180, v253, v0
	v_add_f32_e32 v181, v254, v1
	v_add_f32_e32 v182, v255, v172
	v_add_f32_e32 v187, v179, v173
	v_fma_f32 v188, v134, v183, v180
	v_fma_f32 v189, v134, v184, v181
	v_fma_f32 v190, v134, v185, v182
	v_fma_f32 v203, v134, v186, v187
	v_fma_f32 v204, v135, v191, v188
	v_fma_f32 v205, v135, v192, v189
	v_fma_f32 v206, v135, v193, v190
	v_fma_f32 v175, v135, v194, v203
	s_waitcnt vmcnt(28)
	v_lshlrev_b32_e32 v176, 16, v16
	v_and_b32_e32 v177, s100, v16
	v_lshlrev_b32_e32 v178, 16, v17
	v_and_b32_e32 v183, s100, v17
	v_add_f32_e32 v184, v176, v253
	v_add_f32_e32 v185, v177, v254
	v_add_f32_e32 v186, v178, v255
	v_add_f32_e32 v191, v183, v179
	v_fma_f32 v192, v134, v214, v184
	v_fma_f32 v193, v134, v215, v185
	v_fma_f32 v194, v134, v216, v186
	v_fma_f32 v207, v134, v217, v191
	v_fma_f32 v208, v135, v195, v192
	v_fma_f32 v209, v135, v196, v193
	v_fma_f32 v210, v135, v197, v194
	v_fma_f32 v0, v135, v198, v207
	s_waitcnt vmcnt(27)
	v_lshlrev_b32_e32 v1, 16, v20
	v_and_b32_e32 v172, s100, v20
	v_lshlrev_b32_e32 v173, 16, v21
	v_and_b32_e32 v214, s100, v21
	v_add_f32_e32 v215, v1, v176
	v_add_f32_e32 v216, v172, v177
	v_add_f32_e32 v217, v173, v178
	v_add_f32_e32 v195, v214, v183
	v_fma_f32 v196, v134, v180, v215
	v_fma_f32 v197, v134, v181, v216
	v_fma_f32 v198, v134, v182, v217
	v_fma_f32 v211, v134, v187, v195
	v_fma_f32 v221, v135, v199, v196
	v_fma_f32 v222, v135, v200, v197
	v_fma_f32 v223, v135, v201, v198
	v_fma_f32 v253, v135, v202, v211
	s_waitcnt vmcnt(26)
	v_lshlrev_b32_e32 v254, 16, v24
	v_and_b32_e32 v255, s100, v24
	v_lshlrev_b32_e32 v179, 16, v25
	v_and_b32_e32 v180, s100, v25
	v_add_f32_e32 v181, v254, v1
	v_add_f32_e32 v182, v255, v172
	v_add_f32_e32 v187, v179, v173
	v_add_f32_e32 v199, v180, v214
	v_fma_f32 v200, v134, v184, v181
	v_fma_f32 v201, v134, v185, v182
	v_fma_f32 v202, v134, v186, v187
	v_fma_f32 v224, v134, v191, v199
	v_fma_f32 v225, v135, v244, v200
	v_fma_f32 v226, v135, v245, v201
	v_fma_f32 v227, v135, v246, v202
	v_fma_f32 v176, v135, v247, v224
	s_waitcnt vmcnt(25)
	v_lshlrev_b32_e32 v177, 16, v28
	v_and_b32_e32 v178, s100, v28
	v_lshlrev_b32_e32 v183, 16, v29
	v_and_b32_e32 v184, s100, v29
	v_add_f32_e32 v185, v177, v254
	v_add_f32_e32 v186, v178, v255
	v_add_f32_e32 v191, v183, v179
	v_add_f32_e32 v244, v184, v180
	v_fma_f32 v245, v134, v215, v185
	v_fma_f32 v246, v134, v216, v186
	v_fma_f32 v247, v134, v217, v191
	v_fma_f32 v228, v134, v195, v244
	v_fma_f32 v229, v135, v188, v245
	v_fma_f32 v230, v135, v189, v246
	v_fma_f32 v231, v135, v190, v247
	v_fma_f32 v1, v135, v203, v228
	s_waitcnt vmcnt(24)
	v_lshlrev_b32_e32 v172, 16, v32
	v_and_b32_e32 v173, s100, v32
	v_lshlrev_b32_e32 v214, 16, v33
	v_and_b32_e32 v215, s100, v33
	v_add_f32_e32 v216, v172, v177
	v_add_f32_e32 v217, v173, v178
	v_add_f32_e32 v195, v214, v183
	v_add_f32_e32 v188, v215, v184
	v_fma_f32 v189, v134, v181, v216
	v_fma_f32 v190, v134, v182, v217
	v_fma_f32 v203, v134, v187, v195
	v_fma_f32 v232, v134, v199, v188
	v_fma_f32 v233, v135, v192, v189
	v_fma_f32 v234, v135, v193, v190
	v_fma_f32 v235, v135, v194, v203
	v_fma_f32 v254, v135, v207, v232
	s_waitcnt vmcnt(23)
; __device__ __forceinline__ unsigned pk2(float lo, float hi) { return pg8::cvt_pk_bf16(lo, hi); }
; __global__ void __launch_bounds__(NTHR, 2) hybrid_fwd(Args args) {
;     ...
;         for (int i = 0; i < nr; ++i) { const int t = t_b + i;
;             const int sp = t & 2047, cnt = (sp + 1) < w ? (sp + 1) : w;
;             u32x4 qv[16];
; #pragma unroll
;             for (int j = 0; j < 16; ++j) qv[j] = qn[j];
;             if (i + 1 < nr) { const int t1 = t + 1, sp1 = t1 & 2047, c1_ = (sp1 + 1) < w ? (sp1 + 1) : w;
; #pragma unroll
;                 for (int j = 0; j < 16; ++j) qn[j] = *(const u32x4*)(UB + (size_t)(j < c1_ ? t1 - j : t1) * 512 + lane * 8); }
;             float a[8];
; #pragma unroll
;             for (int e = 0; e < 8; ++e) a[e] = 0.f;
;             const u32x4 u0 = qv[0];
; #pragma unroll
;             for (int j = 0; j < 16; ++j) { const float mk = j < cnt ? 1.0f : 0.0f; const u32x4 q = qv[j];
;                 a[0] += mk * bflo(q.x); a[1] += mk * bfhi(q.x); a[2] += mk * bflo(q.y); a[3] += mk * bfhi(q.y); a[4] += mk * bflo(q.z); a[5] += mk * bfhi(q.z); a[6] += mk * bflo(q.w); a[7] += mk * bfhi(q.w); }
;             const float ic = 1.0f / (float)cnt;
;             u32x4 o; o.x = pk2(a[0] * ic - bflo(u0.x), a[1] * ic - bfhi(u0.x)); o.y = pk2(a[2] * ic - bflo(u0.y), a[3] * ic - bfhi(u0.y));
;             o.z = pk2(a[4] * ic - bflo(u0.z), a[5] * ic - bfhi(u0.z)); o.w = pk2(a[6] * ic - bflo(u0.w), a[7] * ic - bfhi(u0.w));
;             *(u32x4*)(AD + (size_t)t * 1024 + lane * 8) = o; }
	v_lshlrev_b32_e32 v255, 16, v36
	v_and_b32_e32 v179, s100, v36
	v_lshlrev_b32_e32 v180, 16, v37
	v_and_b32_e32 v181, s100, v37
	v_add_f32_e32 v182, v255, v172
	v_add_f32_e32 v187, v179, v173
	v_add_f32_e32 v199, v180, v214
	v_add_f32_e32 v192, v181, v215
	v_fma_f32 v193, v134, v185, v182
	v_fma_f32 v194, v134, v186, v187
	v_fma_f32 v207, v134, v191, v199
	v_fma_f32 v236, v134, v244, v192
	v_fma_f32 v237, v135, v196, v193
	v_fma_f32 v238, v135, v197, v194
	v_fma_f32 v239, v135, v198, v207
	v_fma_f32 v177, v135, v211, v236
	s_waitcnt vmcnt(22)
	v_lshlrev_b32_e32 v178, 16, v40
	v_and_b32_e32 v183, s100, v40
	v_lshlrev_b32_e32 v184, 16, v41
	v_and_b32_e32 v185, s100, v41
	v_add_f32_e32 v186, v178, v255
	v_add_f32_e32 v191, v183, v179
	v_add_f32_e32 v244, v184, v180
	v_add_f32_e32 v196, v185, v181
	v_fma_f32 v197, v134, v216, v186
	v_fma_f32 v198, v134, v217, v191
	v_fma_f32 v211, v134, v195, v244
	v_fma_f32 v240, v134, v188, v196
	v_fma_f32 v241, v135, v200, v197
	v_fma_f32 v242, v135, v201, v198
	v_fma_f32 v243, v135, v202, v211
	v_fma_f32 v172, v135, v224, v240
	s_waitcnt vmcnt(21)
	v_lshlrev_b32_e32 v173, 16, v44
	v_and_b32_e32 v214, s100, v44
	v_lshlrev_b32_e32 v215, 16, v45
	v_and_b32_e32 v216, s100, v45
	v_add_f32_e32 v217, v173, v178
	v_add_f32_e32 v195, v214, v183
	v_add_f32_e32 v188, v215, v184
	v_add_f32_e32 v200, v216, v185
	v_fma_f32 v201, v134, v182, v217
	v_fma_f32 v202, v134, v187, v195
	v_fma_f32 v224, v134, v199, v188
	v_fma_f32 v249, v134, v192, v200
	v_fma_f32 v250, v135, v245, v201
	v_fma_f32 v251, v135, v246, v202
	v_fma_f32 v252, v135, v247, v224
	v_fma_f32 v255, v135, v228, v249
	s_waitcnt vmcnt(20)
	v_lshlrev_b32_e32 v179, 16, v48
	v_and_b32_e32 v180, s100, v48
	v_lshlrev_b32_e32 v181, 16, v49
	v_and_b32_e32 v182, s100, v49
	v_add_f32_e32 v187, v179, v173
	v_add_f32_e32 v199, v180, v214
	v_add_f32_e32 v192, v181, v215
	v_add_f32_e32 v245, v182, v216
	v_fma_f32 v246, v134, v186, v187
	v_fma_f32 v247, v134, v191, v199
	v_fma_f32 v228, v134, v244, v192
	v_fma_f32 v204, v134, v196, v245
	v_fma_f32 v205, v135, v189, v246
	v_fma_f32 v206, v135, v190, v247
	v_fma_f32 v175, v135, v203, v228
	v_fma_f32 v178, v135, v232, v204
	s_waitcnt vmcnt(19)
	v_lshlrev_b32_e32 v183, 16, v52
	v_and_b32_e32 v184, s100, v52
	v_lshlrev_b32_e32 v185, 16, v53
	v_and_b32_e32 v186, s100, v53
	v_add_f32_e32 v191, v183, v179
	v_add_f32_e32 v244, v184, v180
	v_add_f32_e32 v196, v185, v181
	v_add_f32_e32 v189, v186, v182
	v_fma_f32 v190, v134, v217, v191
	v_fma_f32 v203, v134, v195, v244
	v_fma_f32 v232, v134, v188, v196
	v_fma_f32 v208, v134, v200, v189
	v_fma_f32 v209, v135, v193, v190
	v_fma_f32 v210, v135, v194, v203
	v_fma_f32 v0, v135, v207, v232
	v_fma_f32 v173, v135, v236, v208
	s_waitcnt vmcnt(18)
	v_lshlrev_b32_e32 v214, 16, v56
	v_and_b32_e32 v215, s100, v56
	v_lshlrev_b32_e32 v216, 16, v57
	v_and_b32_e32 v217, s100, v57
	v_add_f32_e32 v195, v214, v183
	v_add_f32_e32 v188, v215, v184
	v_add_f32_e32 v200, v216, v185
	v_add_f32_e32 v193, v217, v186
	v_fma_f32 v194, v134, v187, v195
	v_fma_f32 v207, v134, v199, v188
	v_fma_f32 v236, v134, v192, v200
	v_fma_f32 v221, v134, v245, v193
	v_fma_f32 v222, v135, v197, v194
	v_fma_f32 v223, v135, v198, v207
	v_fma_f32 v253, v135, v211, v236
	v_fma_f32 v179, v135, v240, v221
	s_waitcnt vmcnt(17)
	v_lshlrev_b32_e32 v180, 16, v60
	v_and_b32_e32 v181, s100, v60
	v_lshlrev_b32_e32 v182, 16, v61
	v_and_b32_e32 v187, s100, v61
	v_add_f32_e32 v199, v180, v214
	v_add_f32_e32 v192, v181, v215
	v_add_f32_e32 v245, v182, v216
	v_add_f32_e32 v197, v187, v217
	v_fma_f32 v198, v134, v191, v199
	v_fma_f32 v211, v134, v244, v192
	v_fma_f32 v240, v134, v196, v245
	v_fma_f32 v225, v134, v189, v197
	v_fma_f32 v226, v135, v201, v198
	v_fma_f32 v227, v135, v202, v211
	v_fma_f32 v176, v135, v224, v240
	v_fma_f32 v183, v135, v249, v225
	s_waitcnt vmcnt(16)
	v_lshlrev_b32_e32 v184, 16, v64
	v_and_b32_e32 v185, s100, v64
	v_lshlrev_b32_e32 v186, 16, v65
	v_and_b32_e32 v191, s100, v65
	v_add_f32_e32 v244, v184, v180
	v_add_f32_e32 v196, v185, v181
	v_add_f32_e32 v189, v186, v182
	v_add_f32_e32 v201, v191, v187
	v_fma_f32 v202, v134, v195, v244
	v_fma_f32 v224, v134, v188, v196
	v_fma_f32 v249, v134, v200, v189
	v_fma_f32 v229, v134, v193, v201
	v_fma_f32 v230, v135, v246, v202
	v_fma_f32 v231, v135, v247, v224
	v_fma_f32 v1, v135, v228, v249
	v_fma_f32 v214, v135, v204, v229
	s_waitcnt vmcnt(15)
	v_lshlrev_b32_e32 v215, 16, v68
	v_and_b32_e32 v216, s100, v68
	v_lshlrev_b32_e32 v217, 16, v69
	v_and_b32_e32 v195, s100, v69
	v_add_f32_e32 v188, v215, v184
	v_add_f32_e32 v200, v216, v185
	v_add_f32_e32 v193, v217, v186
	v_add_f32_e32 v246, v195, v191
	v_fma_f32 v247, v134, v199, v188
	v_fma_f32 v228, v134, v192, v200
	v_fma_f32 v204, v134, v245, v193
	v_fma_f32 v233, v134, v197, v246
	v_fma_f32 v234, v135, v190, v247
	v_fma_f32 v235, v135, v203, v228
	v_fma_f32 v254, v135, v232, v204
	v_fma_f32 v180, v135, v208, v233
	v_fma_f32 v181, v136, v237, v234
	v_fma_f32 v182, v136, v238, v235
	v_fma_f32 v187, v136, v239, v254
	v_fma_f32 v199, v136, v177, v180
	s_add_i32 s101, s99, 1
	v_min_u32_e32 v192, s101, v137
	v_cvt_f32_u32_e32 v192, v192
	v_rcp_f32_e32 v192, v192
	s_nop 0
	v_fma_f32 v181, v181, v192, -v215
	v_fma_f32 v182, v182, v192, -v216
	v_fma_f32 v187, v187, v192, -v217
	v_fma_f32 v199, v199, v192, -v195
	v_cvt_pk_bf16_f32 v68, v181, v182
	v_cvt_pk_bf16_f32 v69, v187, v199
	s_waitcnt vmcnt(14)
; __device__ __forceinline__ unsigned pk2(float lo, float hi) { return pg8::cvt_pk_bf16(lo, hi); }
; __global__ void __launch_bounds__(NTHR, 2) hybrid_fwd(Args args) {
;     ...
;         for (int i = 0; i < nr; ++i) { const int t = t_b + i;
;             const int sp = t & 2047, cnt = (sp + 1) < w ? (sp + 1) : w;
;             u32x4 qv[16];
; #pragma unroll
;             for (int j = 0; j < 16; ++j) qv[j] = qn[j];
;             if (i + 1 < nr) { const int t1 = t + 1, sp1 = t1 & 2047, c1_ = (sp1 + 1) < w ? (sp1 + 1) : w;
; #pragma unroll
;                 for (int j = 0; j < 16; ++j) qn[j] = *(const u32x4*)(UB + (size_t)(j < c1_ ? t1 - j : t1) * 512 + lane * 8); }
;             float a[8];
; #pragma unroll
;             for (int e = 0; e < 8; ++e) a[e] = 0.f;
;             const u32x4 u0 = qv[0];
; #pragma unroll
;             for (int j = 0; j < 16; ++j) { const float mk = j < cnt ? 1.0f : 0.0f; const u32x4 q = qv[j];
;                 a[0] += mk * bflo(q.x); a[1] += mk * bfhi(q.x); a[2] += mk * bflo(q.y); a[3] += mk * bfhi(q.y); a[4] += mk * bflo(q.z); a[5] += mk * bfhi(q.z); a[6] += mk * bflo(q.w); a[7] += mk * bfhi(q.w); }
;             const float ic = 1.0f / (float)cnt;
;             u32x4 o; o.x = pk2(a[0] * ic - bflo(u0.x), a[1] * ic - bfhi(u0.x)); o.y = pk2(a[2] * ic - bflo(u0.y), a[3] * ic - bfhi(u0.y));
;             o.z = pk2(a[4] * ic - bflo(u0.z), a[5] * ic - bfhi(u0.z)); o.w = pk2(a[6] * ic - bflo(u0.w), a[7] * ic - bfhi(u0.w));
;             *(u32x4*)(AD + (size_t)t * 1024 + lane * 8) = o; }
	v_lshlrev_b32_e32 v245, 16, v72
	v_and_b32_e32 v197, s100, v72
	v_lshlrev_b32_e32 v190, 16, v73
	v_and_b32_e32 v203, s100, v73
	v_add_f32_e32 v232, v245, v215
	v_add_f32_e32 v208, v197, v216
	v_add_f32_e32 v237, v190, v217
	v_add_f32_e32 v238, v203, v195
	v_fma_f32 v239, v134, v244, v232
	v_fma_f32 v177, v134, v196, v208
	v_fma_f32 v181, v134, v189, v237
	v_fma_f32 v182, v134, v201, v238
	v_fma_f32 v187, v135, v194, v239
	v_fma_f32 v199, v135, v207, v177
	v_fma_f32 v192, v135, v236, v181
	v_fma_f32 v184, v135, v221, v182
	v_fma_f32 v185, v136, v241, v187
	v_fma_f32 v186, v136, v242, v199
	v_fma_f32 v191, v136, v243, v192
	v_fma_f32 v244, v136, v172, v184
	s_add_i32 s101, s99, 2
	v_min_u32_e32 v196, s101, v137
	v_cvt_f32_u32_e32 v196, v196
	v_rcp_f32_e32 v196, v196
	s_nop 0
	v_fma_f32 v185, v185, v196, -v245
	v_fma_f32 v186, v186, v196, -v197
	v_fma_f32 v191, v191, v196, -v190
	v_fma_f32 v244, v244, v196, -v203
	v_cvt_pk_bf16_f32 v72, v185, v186
	v_cvt_pk_bf16_f32 v73, v191, v244
	s_waitcnt vmcnt(13)
	v_lshlrev_b32_e32 v189, 16, v76
	v_and_b32_e32 v201, s100, v76
	v_lshlrev_b32_e32 v194, 16, v77
	v_and_b32_e32 v207, s100, v77
	v_add_f32_e32 v236, v189, v245
	v_add_f32_e32 v221, v201, v197
	v_add_f32_e32 v241, v194, v190
	v_add_f32_e32 v242, v207, v203
	v_fma_f32 v243, v134, v188, v236
	v_fma_f32 v172, v134, v200, v221
	v_fma_f32 v185, v134, v193, v241
	v_fma_f32 v186, v134, v246, v242
	v_fma_f32 v191, v135, v198, v243
	v_fma_f32 v244, v135, v211, v172
	v_fma_f32 v196, v135, v240, v185
	v_fma_f32 v215, v135, v225, v186
	v_fma_f32 v216, v136, v250, v191
	v_fma_f32 v217, v136, v251, v244
	v_fma_f32 v195, v136, v252, v196
	v_fma_f32 v188, v136, v255, v215
	s_add_i32 s101, s99, 3
	v_min_u32_e32 v200, s101, v137
	v_cvt_f32_u32_e32 v200, v200
	v_rcp_f32_e32 v200, v200
	s_nop 0
	v_fma_f32 v216, v216, v200, -v189
	v_fma_f32 v217, v217, v200, -v201
	v_fma_f32 v195, v195, v200, -v194
	v_fma_f32 v188, v188, v200, -v207
	v_cvt_pk_bf16_f32 v76, v216, v217
	v_cvt_pk_bf16_f32 v77, v195, v188
	s_waitcnt vmcnt(12)
	v_lshlrev_b32_e32 v193, 16, v80
	v_and_b32_e32 v246, s100, v80
	v_lshlrev_b32_e32 v198, 16, v81
	v_and_b32_e32 v211, s100, v81
	v_add_f32_e32 v240, v193, v189
	v_add_f32_e32 v225, v246, v201
	v_add_f32_e32 v250, v198, v194
	v_add_f32_e32 v251, v211, v207
	v_fma_f32 v252, v134, v232, v240
	v_fma_f32 v255, v134, v208, v225
	v_fma_f32 v216, v134, v237, v250
	v_fma_f32 v217, v134, v238, v251
	v_fma_f32 v195, v135, v202, v252
	v_fma_f32 v188, v135, v224, v255
	v_fma_f32 v200, v135, v249, v216
	v_fma_f32 v245, v135, v229, v217
	v_fma_f32 v197, v136, v205, v195
	v_fma_f32 v190, v136, v206, v188
	v_fma_f32 v203, v136, v175, v200
	v_fma_f32 v232, v136, v178, v245
	s_add_i32 s101, s99, 4
	v_min_u32_e32 v208, s101, v137
	v_cvt_f32_u32_e32 v208, v208
	v_rcp_f32_e32 v208, v208
	s_nop 0
	v_fma_f32 v197, v197, v208, -v193
	v_fma_f32 v190, v190, v208, -v246
	v_fma_f32 v203, v203, v208, -v198
	v_fma_f32 v232, v232, v208, -v211
	v_cvt_pk_bf16_f32 v80, v197, v190
	v_cvt_pk_bf16_f32 v81, v203, v232
	s_waitcnt vmcnt(11)
	v_lshlrev_b32_e32 v237, 16, v84
	v_and_b32_e32 v238, s100, v84
	v_lshlrev_b32_e32 v202, 16, v85
	v_and_b32_e32 v224, s100, v85
	v_add_f32_e32 v249, v237, v193
	v_add_f32_e32 v229, v238, v246
	v_add_f32_e32 v205, v202, v198
	v_add_f32_e32 v206, v224, v211
	v_fma_f32 v175, v134, v236, v249
	v_fma_f32 v178, v134, v221, v229
	v_fma_f32 v197, v134, v241, v205
	v_fma_f32 v190, v134, v242, v206
	v_fma_f32 v203, v135, v247, v175
	v_fma_f32 v232, v135, v228, v178
	v_fma_f32 v208, v135, v204, v197
	v_fma_f32 v189, v135, v233, v190
	v_fma_f32 v201, v136, v209, v203
	v_fma_f32 v194, v136, v210, v232
	v_fma_f32 v207, v136, v0, v208
	v_fma_f32 v236, v136, v173, v189
	s_add_i32 s101, s99, 5
	v_min_u32_e32 v221, s101, v137
	v_cvt_f32_u32_e32 v221, v221
	v_rcp_f32_e32 v221, v221
	s_nop 0
	v_fma_f32 v201, v201, v221, -v237
	v_fma_f32 v194, v194, v221, -v238
	v_fma_f32 v207, v207, v221, -v202
	v_fma_f32 v236, v236, v221, -v224
	v_cvt_pk_bf16_f32 v84, v201, v194
	v_cvt_pk_bf16_f32 v85, v207, v236
	s_waitcnt vmcnt(10)
	v_lshlrev_b32_e32 v241, 16, v88
	v_and_b32_e32 v242, s100, v88
	v_lshlrev_b32_e32 v247, 16, v89
	v_and_b32_e32 v228, s100, v89
	v_add_f32_e32 v204, v241, v237
	v_add_f32_e32 v233, v242, v238
	v_add_f32_e32 v209, v247, v202
	v_add_f32_e32 v210, v228, v224
	v_fma_f32 v0, v134, v240, v204
	v_fma_f32 v173, v134, v225, v233
	v_fma_f32 v201, v134, v250, v209
	v_fma_f32 v194, v134, v251, v210
	v_fma_f32 v207, v135, v239, v0
	v_fma_f32 v236, v135, v177, v173
	v_fma_f32 v221, v135, v181, v201
	v_fma_f32 v193, v135, v182, v194
	v_fma_f32 v246, v136, v222, v207
	v_fma_f32 v198, v136, v223, v236
	v_fma_f32 v211, v136, v253, v221
	v_fma_f32 v240, v136, v179, v193
	s_add_i32 s101, s99, 6
	v_min_u32_e32 v225, s101, v137
	v_cvt_f32_u32_e32 v225, v225
	v_rcp_f32_e32 v225, v225
	s_nop 0
	v_fma_f32 v246, v246, v225, -v241
	v_fma_f32 v198, v198, v225, -v242
	v_fma_f32 v211, v211, v225, -v247
	v_fma_f32 v240, v240, v225, -v228
	v_cvt_pk_bf16_f32 v88, v246, v198
	v_cvt_pk_bf16_f32 v89, v211, v240
	s_waitcnt vmcnt(9)
	v_lshlrev_b32_e32 v250, 16, v92
	v_and_b32_e32 v251, s100, v92
	v_lshlrev_b32_e32 v239, 16, v93
	v_and_b32_e32 v177, s100, v93
	v_add_f32_e32 v181, v250, v241
	v_add_f32_e32 v182, v251, v242
	v_add_f32_e32 v222, v239, v247
	v_add_f32_e32 v223, v177, v228
	v_fma_f32 v253, v134, v249, v181
	v_fma_f32 v179, v134, v229, v182
	v_fma_f32 v246, v134, v205, v222
	v_fma_f32 v198, v134, v206, v223
	v_fma_f32 v211, v135, v243, v253
	v_fma_f32 v240, v135, v172, v179
	v_fma_f32 v225, v135, v185, v246
	v_fma_f32 v237, v135, v186, v198
	v_fma_f32 v238, v136, v226, v211
	v_fma_f32 v202, v136, v227, v240
	v_fma_f32 v224, v136, v176, v225
	v_fma_f32 v249, v136, v183, v237
	s_add_i32 s101, s99, 7
	v_min_u32_e32 v229, s101, v137
	v_cvt_f32_u32_e32 v229, v229
	v_rcp_f32_e32 v229, v229
	s_nop 0
	v_fma_f32 v238, v238, v229, -v250
	v_fma_f32 v202, v202, v229, -v251
	v_fma_f32 v224, v224, v229, -v239
	v_fma_f32 v249, v249, v229, -v177
	v_cvt_pk_bf16_f32 v92, v238, v202
	v_cvt_pk_bf16_f32 v93, v224, v249
	s_waitcnt vmcnt(8)
; __device__ __forceinline__ unsigned pk2(float lo, float hi) { return pg8::cvt_pk_bf16(lo, hi); }
; __global__ void __launch_bounds__(NTHR, 2) hybrid_fwd(Args args) {
;     ...
;         for (int i = 0; i < nr; ++i) { const int t = t_b + i;
;             const int sp = t & 2047, cnt = (sp + 1) < w ? (sp + 1) : w;
;             u32x4 qv[16];
; #pragma unroll
;             for (int j = 0; j < 16; ++j) qv[j] = qn[j];
;             if (i + 1 < nr) { const int t1 = t + 1, sp1 = t1 & 2047, c1_ = (sp1 + 1) < w ? (sp1 + 1) : w;
; #pragma unroll
;                 for (int j = 0; j < 16; ++j) qn[j] = *(const u32x4*)(UB + (size_t)(j < c1_ ? t1 - j : t1) * 512 + lane * 8); }
;             float a[8];
; #pragma unroll
;             for (int e = 0; e < 8; ++e) a[e] = 0.f;
;             const u32x4 u0 = qv[0];
; #pragma unroll
;             for (int j = 0; j < 16; ++j) { const float mk = j < cnt ? 1.0f : 0.0f; const u32x4 q = qv[j];
;                 a[0] += mk * bflo(q.x); a[1] += mk * bfhi(q.x); a[2] += mk * bflo(q.y); a[3] += mk * bfhi(q.y); a[4] += mk * bflo(q.z); a[5] += mk * bfhi(q.z); a[6] += mk * bflo(q.w); a[7] += mk * bfhi(q.w); }
;             const float ic = 1.0f / (float)cnt;
;             u32x4 o; o.x = pk2(a[0] * ic - bflo(u0.x), a[1] * ic - bfhi(u0.x)); o.y = pk2(a[2] * ic - bflo(u0.y), a[3] * ic - bfhi(u0.y));
;             o.z = pk2(a[4] * ic - bflo(u0.z), a[5] * ic - bfhi(u0.z)); o.w = pk2(a[6] * ic - bflo(u0.w), a[7] * ic - bfhi(u0.w));
;             *(u32x4*)(AD + (size_t)t * 1024 + lane * 8) = o; }
	v_lshlrev_b32_e32 v205, 16, v96
	v_and_b32_e32 v206, s100, v96
	v_lshlrev_b32_e32 v243, 16, v97
	v_and_b32_e32 v172, s100, v97
	v_add_f32_e32 v185, v205, v250
	v_add_f32_e32 v186, v206, v251
	v_add_f32_e32 v226, v243, v239
	v_add_f32_e32 v227, v172, v177
	v_fma_f32 v176, v134, v204, v185
	v_fma_f32 v183, v134, v233, v186
	v_fma_f32 v238, v134, v209, v226
	v_fma_f32 v202, v134, v210, v227
	v_fma_f32 v224, v135, v252, v176
	v_fma_f32 v249, v135, v255, v183
	v_fma_f32 v229, v135, v216, v238
	v_fma_f32 v241, v135, v217, v202
	v_fma_f32 v242, v136, v230, v224
	v_fma_f32 v247, v136, v231, v249
	v_fma_f32 v228, v136, v1, v229
	v_fma_f32 v204, v136, v214, v241
	s_add_i32 s101, s99, 8
	v_min_u32_e32 v233, s101, v137
	v_cvt_f32_u32_e32 v233, v233
	v_rcp_f32_e32 v233, v233
	s_nop 0
	v_fma_f32 v242, v242, v233, -v205
	v_fma_f32 v247, v247, v233, -v206
	v_fma_f32 v228, v228, v233, -v243
	v_fma_f32 v204, v204, v233, -v172
	v_cvt_pk_bf16_f32 v96, v242, v247
	v_cvt_pk_bf16_f32 v97, v228, v204
	s_waitcnt vmcnt(7)
	v_lshlrev_b32_e32 v209, 16, v100
	v_and_b32_e32 v210, s100, v100
	v_lshlrev_b32_e32 v252, 16, v101
	v_and_b32_e32 v255, s100, v101
	v_add_f32_e32 v216, v209, v205
	v_add_f32_e32 v217, v210, v206
	v_add_f32_e32 v230, v252, v243
	v_add_f32_e32 v231, v255, v172
	v_fma_f32 v1, v134, v181, v216
	v_fma_f32 v214, v134, v182, v217
	v_fma_f32 v242, v134, v222, v230
	v_fma_f32 v247, v134, v223, v231
	v_fma_f32 v228, v135, v175, v1
	v_fma_f32 v204, v135, v178, v214
	v_fma_f32 v233, v135, v197, v242
	v_fma_f32 v250, v135, v190, v247
	v_fma_f32 v251, v136, v234, v228
	v_fma_f32 v239, v136, v235, v204
	v_fma_f32 v177, v136, v254, v233
	v_fma_f32 v181, v136, v180, v250
	s_add_i32 s101, s99, 9
	v_min_u32_e32 v182, s101, v137
	v_cvt_f32_u32_e32 v182, v182
	v_rcp_f32_e32 v182, v182
	s_nop 0
	v_fma_f32 v251, v251, v182, -v209
	v_fma_f32 v239, v239, v182, -v210
	v_fma_f32 v177, v177, v182, -v252
	v_fma_f32 v181, v181, v182, -v255
	v_cvt_pk_bf16_f32 v100, v251, v239
	v_cvt_pk_bf16_f32 v101, v177, v181
	s_waitcnt vmcnt(6)
	v_lshlrev_b32_e32 v222, 16, v104
	v_and_b32_e32 v223, s100, v104
	v_lshlrev_b32_e32 v175, 16, v105
	v_and_b32_e32 v178, s100, v105
	v_add_f32_e32 v197, v222, v209
	v_add_f32_e32 v190, v223, v210
	v_add_f32_e32 v234, v175, v252
	v_add_f32_e32 v235, v178, v255
	v_fma_f32 v254, v134, v185, v197
	v_fma_f32 v180, v134, v186, v190
	v_fma_f32 v251, v134, v226, v234
	v_fma_f32 v239, v134, v227, v235
	v_fma_f32 v177, v135, v0, v254
	v_fma_f32 v181, v135, v173, v180
	v_fma_f32 v182, v135, v201, v251
	v_fma_f32 v205, v135, v194, v239
	v_fma_f32 v206, v136, v187, v177
	v_fma_f32 v243, v136, v199, v181
	v_fma_f32 v172, v136, v192, v182
	v_fma_f32 v185, v136, v184, v205
	s_add_i32 s101, s99, 10
	v_min_u32_e32 v186, s101, v137
	v_cvt_f32_u32_e32 v186, v186
	v_rcp_f32_e32 v186, v186
	s_nop 0
	v_fma_f32 v206, v206, v186, -v222
	v_fma_f32 v243, v243, v186, -v223
	v_fma_f32 v172, v172, v186, -v175
	v_fma_f32 v185, v185, v186, -v178
	v_cvt_pk_bf16_f32 v104, v206, v243
	v_cvt_pk_bf16_f32 v105, v172, v185
	s_waitcnt vmcnt(5)
	v_lshlrev_b32_e32 v226, 16, v108
	v_and_b32_e32 v227, s100, v108
	v_lshlrev_b32_e32 v0, 16, v109
	v_and_b32_e32 v173, s100, v109
	v_add_f32_e32 v201, v226, v222
	v_add_f32_e32 v194, v227, v223
	v_add_f32_e32 v187, v0, v175
	v_add_f32_e32 v199, v173, v178
	v_fma_f32 v192, v134, v216, v201
	v_fma_f32 v184, v134, v217, v194
	v_fma_f32 v206, v134, v230, v187
	v_fma_f32 v243, v134, v231, v199
	v_fma_f32 v172, v135, v253, v192
	v_fma_f32 v185, v135, v179, v184
	v_fma_f32 v186, v135, v246, v206
	v_fma_f32 v209, v135, v198, v243
	v_fma_f32 v210, v136, v191, v172
	v_fma_f32 v252, v136, v244, v185
	v_fma_f32 v255, v136, v196, v186
	v_fma_f32 v216, v136, v215, v209
	s_add_i32 s101, s99, 11
	v_min_u32_e32 v217, s101, v137
	v_cvt_f32_u32_e32 v217, v217
	v_rcp_f32_e32 v217, v217
	s_nop 0
	v_fma_f32 v210, v210, v217, -v226
	v_fma_f32 v252, v252, v217, -v227
	v_fma_f32 v255, v255, v217, -v0
	v_fma_f32 v216, v216, v217, -v173
	v_cvt_pk_bf16_f32 v108, v210, v252
	v_cvt_pk_bf16_f32 v109, v255, v216
	s_waitcnt vmcnt(4)
	v_lshlrev_b32_e32 v230, 16, v112
	v_and_b32_e32 v231, s100, v112
	v_lshlrev_b32_e32 v253, 16, v113
	v_and_b32_e32 v179, s100, v113
	v_add_f32_e32 v246, v230, v226
	v_add_f32_e32 v198, v231, v227
	v_add_f32_e32 v191, v253, v0
	v_add_f32_e32 v244, v179, v173
	v_fma_f32 v196, v134, v197, v246
	v_fma_f32 v215, v134, v190, v198
	v_fma_f32 v210, v134, v234, v191
	v_fma_f32 v252, v134, v235, v244
	v_fma_f32 v255, v135, v176, v196
	v_fma_f32 v216, v135, v183, v215
	v_fma_f32 v217, v135, v238, v210
	v_fma_f32 v222, v135, v202, v252
	v_fma_f32 v223, v136, v195, v255
	v_fma_f32 v175, v136, v188, v216
	v_fma_f32 v178, v136, v200, v217
	v_fma_f32 v197, v136, v245, v222
	s_add_i32 s101, s99, 12
	v_min_u32_e32 v190, s101, v137
	v_cvt_f32_u32_e32 v190, v190
	v_rcp_f32_e32 v190, v190
	s_nop 0
	v_fma_f32 v223, v223, v190, -v230
	v_fma_f32 v175, v175, v190, -v231
	v_fma_f32 v178, v178, v190, -v253
	v_fma_f32 v197, v197, v190, -v179
	v_cvt_pk_bf16_f32 v112, v223, v175
	v_cvt_pk_bf16_f32 v113, v178, v197
	s_waitcnt vmcnt(3)
	v_lshlrev_b32_e32 v234, 16, v116
	v_and_b32_e32 v235, s100, v116
	v_lshlrev_b32_e32 v176, 16, v117
	v_and_b32_e32 v183, s100, v117
	v_add_f32_e32 v238, v234, v230
	v_add_f32_e32 v202, v235, v231
	v_add_f32_e32 v195, v176, v253
	v_add_f32_e32 v188, v183, v179
	v_fma_f32 v200, v134, v201, v238
	v_fma_f32 v245, v134, v194, v202
	v_fma_f32 v223, v134, v187, v195
	v_fma_f32 v175, v134, v199, v188
	v_fma_f32 v178, v135, v1, v200
	v_fma_f32 v197, v135, v214, v245
	v_fma_f32 v190, v135, v242, v223
	v_fma_f32 v226, v135, v247, v175
	v_fma_f32 v227, v136, v203, v178
	v_fma_f32 v0, v136, v232, v197
	v_fma_f32 v173, v136, v208, v190
	v_fma_f32 v201, v136, v189, v226
	s_add_i32 s101, s99, 13
	v_min_u32_e32 v194, s101, v137
	v_cvt_f32_u32_e32 v194, v194
	v_rcp_f32_e32 v194, v194
	s_nop 0
	v_fma_f32 v227, v227, v194, -v234
	v_fma_f32 v0, v0, v194, -v235
	v_fma_f32 v173, v173, v194, -v176
	v_fma_f32 v201, v201, v194, -v183
	v_cvt_pk_bf16_f32 v116, v227, v0
	v_cvt_pk_bf16_f32 v117, v173, v201
	s_waitcnt vmcnt(2)
; __device__ __forceinline__ unsigned pk2(float lo, float hi) { return pg8::cvt_pk_bf16(lo, hi); }
; __global__ void __launch_bounds__(NTHR, 2) hybrid_fwd(Args args) {
;     ...
;         for (int i = 0; i < nr; ++i) { const int t = t_b + i;
;             const int sp = t & 2047, cnt = (sp + 1) < w ? (sp + 1) : w;
;             u32x4 qv[16];
; #pragma unroll
;             for (int j = 0; j < 16; ++j) qv[j] = qn[j];
;             if (i + 1 < nr) { const int t1 = t + 1, sp1 = t1 & 2047, c1_ = (sp1 + 1) < w ? (sp1 + 1) : w;
; #pragma unroll
;                 for (int j = 0; j < 16; ++j) qn[j] = *(const u32x4*)(UB + (size_t)(j < c1_ ? t1 - j : t1) * 512 + lane * 8); }
;             float a[8];
; #pragma unroll
;             for (int e = 0; e < 8; ++e) a[e] = 0.f;
;             const u32x4 u0 = qv[0];
; #pragma unroll
;             for (int j = 0; j < 16; ++j) { const float mk = j < cnt ? 1.0f : 0.0f; const u32x4 q = qv[j];
;                 a[0] += mk * bflo(q.x); a[1] += mk * bfhi(q.x); a[2] += mk * bflo(q.y); a[3] += mk * bfhi(q.y); a[4] += mk * bflo(q.z); a[5] += mk * bfhi(q.z); a[6] += mk * bflo(q.w); a[7] += mk * bfhi(q.w); }
;             const float ic = 1.0f / (float)cnt;
;             u32x4 o; o.x = pk2(a[0] * ic - bflo(u0.x), a[1] * ic - bfhi(u0.x)); o.y = pk2(a[2] * ic - bflo(u0.y), a[3] * ic - bfhi(u0.y));
;             o.z = pk2(a[4] * ic - bflo(u0.z), a[5] * ic - bfhi(u0.z)); o.w = pk2(a[6] * ic - bflo(u0.w), a[7] * ic - bfhi(u0.w));
;             *(u32x4*)(AD + (size_t)t * 1024 + lane * 8) = o; }
	v_lshlrev_b32_e32 v187, 16, v120
	v_and_b32_e32 v199, s100, v120
	v_lshlrev_b32_e32 v1, 16, v121
	v_and_b32_e32 v214, s100, v121
	v_add_f32_e32 v242, v187, v234
	v_add_f32_e32 v247, v199, v235
	v_add_f32_e32 v203, v1, v176
	v_add_f32_e32 v232, v214, v183
	v_fma_f32 v208, v134, v246, v242
	v_fma_f32 v189, v134, v198, v247
	v_fma_f32 v227, v134, v191, v203
	v_fma_f32 v0, v134, v244, v232
	v_fma_f32 v173, v135, v254, v208
	v_fma_f32 v201, v135, v180, v189
	v_fma_f32 v194, v135, v251, v227
	v_fma_f32 v230, v135, v239, v0
	v_fma_f32 v231, v136, v207, v173
	v_fma_f32 v253, v136, v236, v201
	v_fma_f32 v179, v136, v221, v194
	v_fma_f32 v246, v136, v193, v230
	s_add_i32 s101, s99, 14
	v_min_u32_e32 v198, s101, v137
	v_cvt_f32_u32_e32 v198, v198
	v_rcp_f32_e32 v198, v198
	s_nop 0
	v_fma_f32 v231, v231, v198, -v187
	v_fma_f32 v253, v253, v198, -v199
	v_fma_f32 v179, v179, v198, -v1
	v_fma_f32 v246, v246, v198, -v214
	v_cvt_pk_bf16_f32 v120, v231, v253
	v_cvt_pk_bf16_f32 v121, v179, v246
	s_waitcnt vmcnt(1)
	v_lshlrev_b32_e32 v191, 16, v124
	v_and_b32_e32 v244, s100, v124
	v_lshlrev_b32_e32 v254, 16, v125
	v_and_b32_e32 v180, s100, v125
	v_add_f32_e32 v251, v191, v187
	v_add_f32_e32 v239, v244, v199
	v_add_f32_e32 v207, v254, v1
	v_add_f32_e32 v236, v180, v214
	v_fma_f32 v221, v134, v238, v251
	v_fma_f32 v193, v134, v202, v239
	v_fma_f32 v231, v134, v195, v207
	v_fma_f32 v253, v134, v188, v236
	v_fma_f32 v179, v135, v192, v221
	v_fma_f32 v246, v135, v184, v193
	v_fma_f32 v198, v135, v206, v231
	v_fma_f32 v234, v135, v243, v253
	v_fma_f32 v235, v136, v211, v179
	v_fma_f32 v176, v136, v240, v246
	v_fma_f32 v183, v136, v225, v198
	v_fma_f32 v238, v136, v237, v234
	s_add_i32 s101, s99, 15
	v_min_u32_e32 v202, s101, v137
	v_cvt_f32_u32_e32 v202, v202
	v_rcp_f32_e32 v202, v202
	s_nop 0
	v_fma_f32 v235, v235, v202, -v191
	v_fma_f32 v176, v176, v202, -v244
	v_fma_f32 v183, v183, v202, -v254
	v_fma_f32 v238, v238, v202, -v180
	v_cvt_pk_bf16_f32 v124, v235, v176
	v_cvt_pk_bf16_f32 v125, v183, v238
	s_waitcnt vmcnt(0)
	v_lshlrev_b32_e32 v195, 16, v128
	v_and_b32_e32 v188, s100, v128
	v_lshlrev_b32_e32 v192, 16, v129
	v_and_b32_e32 v184, s100, v129
	v_add_f32_e32 v206, v195, v191
	v_add_f32_e32 v243, v188, v244
	v_add_f32_e32 v211, v192, v254
	v_add_f32_e32 v240, v184, v180
	v_fma_f32 v225, v134, v242, v206
	v_fma_f32 v237, v134, v247, v243
	v_fma_f32 v235, v134, v203, v211
	v_fma_f32 v176, v134, v232, v240
	v_fma_f32 v183, v135, v196, v225
	v_fma_f32 v238, v135, v215, v237
	v_fma_f32 v202, v135, v210, v235
	v_fma_f32 v187, v135, v252, v176
	v_fma_f32 v199, v136, v224, v183
	v_fma_f32 v1, v136, v249, v238
	v_fma_f32 v214, v136, v229, v202
	v_fma_f32 v242, v136, v241, v187
	s_add_i32 s101, s99, 16
	v_min_u32_e32 v247, s101, v137
	v_cvt_f32_u32_e32 v247, v247
	v_rcp_f32_e32 v247, v247
	s_nop 0
	v_fma_f32 v199, v199, v247, -v195
	v_fma_f32 v1, v1, v247, -v188
	v_fma_f32 v214, v214, v247, -v192
	v_fma_f32 v242, v242, v247, -v184
	v_cvt_pk_bf16_f32 v128, v199, v1
	v_cvt_pk_bf16_f32 v129, v214, v242
	v_mov_b32_e32 v175, 0
	v_mov_b32_e32 v176, 0
	v_mov_b32_e32 v177, 0
	v_mov_b32_e32 v178, 0
	v_mov_b32_e32 v179, 0
	v_mov_b32_e32 v180, 0
	v_mov_b32_e32 v181, 0
	v_mov_b32_e32 v182, 0
	v_mov_b32_e32 v183, 0
	v_mov_b32_e32 v184, 0
	v_mov_b32_e32 v185, 0
	v_mov_b32_e32 v186, 0
	v_mov_b32_e32 v187, 0
	v_mov_b32_e32 v188, 0
	v_mov_b32_e32 v189, 0
	v_mov_b32_e32 v190, 0
	v_mov_b32_e32 v191, 0
	v_mov_b32_e32 v192, 0
	v_mov_b32_e32 v193, 0
	v_mov_b32_e32 v194, 0
	v_mov_b32_e32 v195, 0
	v_mov_b32_e32 v196, 0
	v_mov_b32_e32 v197, 0
	v_mov_b32_e32 v198, 0
	v_mov_b32_e32 v199, 0
	v_mov_b32_e32 v200, 0
	v_mov_b32_e32 v201, 0
	v_mov_b32_e32 v202, 0
	v_mov_b32_e32 v203, 0
	v_mov_b32_e32 v204, 0
	v_mov_b32_e32 v205, 0
	v_mov_b32_e32 v206, 0
	v_mov_b32_e32 v207, 0
	v_mov_b32_e32 v208, 0
	v_mov_b32_e32 v209, 0
	v_mov_b32_e32 v210, 0
	v_mov_b32_e32 v211, 0
	v_mov_b32_e32 v221, 0
	v_mov_b32_e32 v222, 0
	v_mov_b32_e32 v223, 0
	v_mov_b32_e32 v224, 0
	v_mov_b32_e32 v225, 0
	v_mov_b32_e32 v226, 0
	v_mov_b32_e32 v227, 0
	v_mov_b32_e32 v228, 0
	v_mov_b32_e32 v229, 0
	v_mov_b32_e32 v230, 0
	v_mov_b32_e32 v231, 0
	v_mov_b32_e32 v232, 0
	v_mov_b32_e32 v233, 0
	v_mov_b32_e32 v234, 0
	v_mov_b32_e32 v235, 0
	v_mov_b32_e32 v236, 0
	v_mov_b32_e32 v237, 0
	v_mov_b32_e32 v238, 0
	v_mov_b32_e32 v239, 0
	v_mov_b32_e32 v240, 0
	v_mov_b32_e32 v241, 0
	v_mov_b32_e32 v242, 0
	v_mov_b32_e32 v243, 0
	v_lshlrev_b32_e32 v0, 16, v10
	v_and_b32_e32 v1, s100, v10
	v_lshlrev_b32_e32 v172, 16, v11
	v_and_b32_e32 v173, s100, v11
	v_add_f32_e32 v214, v0, v175
	v_add_f32_e32 v215, v1, v176
	v_add_f32_e32 v216, v172, v177
	v_add_f32_e32 v217, v173, v178
	v_fma_f32 v244, v134, v179, v214
	v_fma_f32 v245, v134, v180, v215
	v_fma_f32 v246, v134, v181, v216
	v_fma_f32 v247, v134, v182, v217
	v_fma_f32 v249, v135, v187, v244
	v_fma_f32 v250, v135, v188, v245
	v_fma_f32 v251, v135, v189, v246
	v_fma_f32 v252, v135, v190, v247
	v_lshlrev_b32_e32 v253, 16, v14
	v_and_b32_e32 v254, s100, v14
	v_lshlrev_b32_e32 v255, 16, v15
	v_and_b32_e32 v179, s100, v15
	v_add_f32_e32 v180, v253, v0
	v_add_f32_e32 v181, v254, v1
	v_add_f32_e32 v182, v255, v172
	v_add_f32_e32 v187, v179, v173
	v_fma_f32 v188, v134, v183, v180
	v_fma_f32 v189, v134, v184, v181
	v_fma_f32 v190, v134, v185, v182
	v_fma_f32 v203, v134, v186, v187
	v_fma_f32 v204, v135, v191, v188
	v_fma_f32 v205, v135, v192, v189
	v_fma_f32 v206, v135, v193, v190
	v_fma_f32 v175, v135, v194, v203
	v_lshlrev_b32_e32 v176, 16, v18
	v_and_b32_e32 v177, s100, v18
	v_lshlrev_b32_e32 v178, 16, v19
	v_and_b32_e32 v183, s100, v19
	v_add_f32_e32 v184, v176, v253
	v_add_f32_e32 v185, v177, v254
; __device__ __forceinline__ unsigned pk2(float lo, float hi) { return pg8::cvt_pk_bf16(lo, hi); }
; __global__ void __launch_bounds__(NTHR, 2) hybrid_fwd(Args args) {
;     ...
;         for (int i = 0; i < nr; ++i) { const int t = t_b + i;
;             const int sp = t & 2047, cnt = (sp + 1) < w ? (sp + 1) : w;
;             u32x4 qv[16];
; #pragma unroll
;             for (int j = 0; j < 16; ++j) qv[j] = qn[j];
;             if (i + 1 < nr) { const int t1 = t + 1, sp1 = t1 & 2047, c1_ = (sp1 + 1) < w ? (sp1 + 1) : w;
; #pragma unroll
;                 for (int j = 0; j < 16; ++j) qn[j] = *(const u32x4*)(UB + (size_t)(j < c1_ ? t1 - j : t1) * 512 + lane * 8); }
;             float a[8];
; #pragma unroll
;             for (int e = 0; e < 8; ++e) a[e] = 0.f;
;             const u32x4 u0 = qv[0];
; #pragma unroll
;             for (int j = 0; j < 16; ++j) { const float mk = j < cnt ? 1.0f : 0.0f; const u32x4 q = qv[j];
;                 a[0] += mk * bflo(q.x); a[1] += mk * bfhi(q.x); a[2] += mk * bflo(q.y); a[3] += mk * bfhi(q.y); a[4] += mk * bflo(q.z); a[5] += mk * bfhi(q.z); a[6] += mk * bflo(q.w); a[7] += mk * bfhi(q.w); }
;             const float ic = 1.0f / (float)cnt;
;             u32x4 o; o.x = pk2(a[0] * ic - bflo(u0.x), a[1] * ic - bfhi(u0.x)); o.y = pk2(a[2] * ic - bflo(u0.y), a[3] * ic - bfhi(u0.y));
;             o.z = pk2(a[4] * ic - bflo(u0.z), a[5] * ic - bfhi(u0.z)); o.w = pk2(a[6] * ic - bflo(u0.w), a[7] * ic - bfhi(u0.w));
;             *(u32x4*)(AD + (size_t)t * 1024 + lane * 8) = o; }
	v_add_f32_e32 v186, v178, v255
	v_add_f32_e32 v191, v183, v179
	v_fma_f32 v192, v134, v214, v184
	v_fma_f32 v193, v134, v215, v185
	v_fma_f32 v194, v134, v216, v186
	v_fma_f32 v207, v134, v217, v191
	v_fma_f32 v208, v135, v195, v192
	v_fma_f32 v209, v135, v196, v193
	v_fma_f32 v210, v135, v197, v194
	v_fma_f32 v0, v135, v198, v207
	v_lshlrev_b32_e32 v1, 16, v22
	v_and_b32_e32 v172, s100, v22
	v_lshlrev_b32_e32 v173, 16, v23
	v_and_b32_e32 v214, s100, v23
	v_add_f32_e32 v215, v1, v176
	v_add_f32_e32 v216, v172, v177
	v_add_f32_e32 v217, v173, v178
	v_add_f32_e32 v195, v214, v183
	v_fma_f32 v196, v134, v180, v215
	v_fma_f32 v197, v134, v181, v216
	v_fma_f32 v198, v134, v182, v217
	v_fma_f32 v211, v134, v187, v195
	v_fma_f32 v221, v135, v199, v196
	v_fma_f32 v222, v135, v200, v197
	v_fma_f32 v223, v135, v201, v198
	v_fma_f32 v253, v135, v202, v211
	v_lshlrev_b32_e32 v254, 16, v26
	v_and_b32_e32 v255, s100, v26
	v_lshlrev_b32_e32 v179, 16, v27
	v_and_b32_e32 v180, s100, v27
	v_add_f32_e32 v181, v254, v1
	v_add_f32_e32 v182, v255, v172
	v_add_f32_e32 v187, v179, v173
	v_add_f32_e32 v199, v180, v214
	v_fma_f32 v200, v134, v184, v181
	v_fma_f32 v201, v134, v185, v182
	v_fma_f32 v202, v134, v186, v187
	v_fma_f32 v224, v134, v191, v199
	v_fma_f32 v225, v135, v244, v200
	v_fma_f32 v226, v135, v245, v201
	v_fma_f32 v227, v135, v246, v202
	v_fma_f32 v176, v135, v247, v224
	v_lshlrev_b32_e32 v177, 16, v30
	v_and_b32_e32 v178, s100, v30
	v_lshlrev_b32_e32 v183, 16, v31
	v_and_b32_e32 v184, s100, v31
	v_add_f32_e32 v185, v177, v254
	v_add_f32_e32 v186, v178, v255
	v_add_f32_e32 v191, v183, v179
	v_add_f32_e32 v244, v184, v180
	v_fma_f32 v245, v134, v215, v185
	v_fma_f32 v246, v134, v216, v186
	v_fma_f32 v247, v134, v217, v191
	v_fma_f32 v228, v134, v195, v244
	v_fma_f32 v229, v135, v188, v245
	v_fma_f32 v230, v135, v189, v246
	v_fma_f32 v231, v135, v190, v247
	v_fma_f32 v1, v135, v203, v228
	v_lshlrev_b32_e32 v172, 16, v34
	v_and_b32_e32 v173, s100, v34
	v_lshlrev_b32_e32 v214, 16, v35
	v_and_b32_e32 v215, s100, v35
	v_add_f32_e32 v216, v172, v177
	v_add_f32_e32 v217, v173, v178
	v_add_f32_e32 v195, v214, v183
	v_add_f32_e32 v188, v215, v184
	v_fma_f32 v189, v134, v181, v216
	v_fma_f32 v190, v134, v182, v217
	v_fma_f32 v203, v134, v187, v195
	v_fma_f32 v232, v134, v199, v188
	v_fma_f32 v233, v135, v192, v189
	v_fma_f32 v234, v135, v193, v190
	v_fma_f32 v235, v135, v194, v203
	v_fma_f32 v254, v135, v207, v232
	v_lshlrev_b32_e32 v255, 16, v38
	v_and_b32_e32 v179, s100, v38
	v_lshlrev_b32_e32 v180, 16, v39
	v_and_b32_e32 v181, s100, v39
	v_add_f32_e32 v182, v255, v172
	v_add_f32_e32 v187, v179, v173
	v_add_f32_e32 v199, v180, v214
	v_add_f32_e32 v192, v181, v215
	v_fma_f32 v193, v134, v185, v182
	v_fma_f32 v194, v134, v186, v187
	v_fma_f32 v207, v134, v191, v199
	v_fma_f32 v236, v134, v244, v192
	v_fma_f32 v237, v135, v196, v193
	v_fma_f32 v238, v135, v197, v194
	v_fma_f32 v239, v135, v198, v207
	v_fma_f32 v177, v135, v211, v236
	v_lshlrev_b32_e32 v178, 16, v42
	v_and_b32_e32 v183, s100, v42
	v_lshlrev_b32_e32 v184, 16, v43
	v_and_b32_e32 v185, s100, v43
	v_add_f32_e32 v186, v178, v255
	v_add_f32_e32 v191, v183, v179
	v_add_f32_e32 v244, v184, v180
	v_add_f32_e32 v196, v185, v181
	v_fma_f32 v197, v134, v216, v186
	v_fma_f32 v198, v134, v217, v191
	v_fma_f32 v211, v134, v195, v244
	v_fma_f32 v240, v134, v188, v196
	v_fma_f32 v241, v135, v200, v197
	v_fma_f32 v242, v135, v201, v198
	v_fma_f32 v243, v135, v202, v211
	v_fma_f32 v172, v135, v224, v240
	v_lshlrev_b32_e32 v173, 16, v46
	v_and_b32_e32 v214, s100, v46
	v_lshlrev_b32_e32 v215, 16, v47
	v_and_b32_e32 v216, s100, v47
	v_add_f32_e32 v217, v173, v178
	v_add_f32_e32 v195, v214, v183
	v_add_f32_e32 v188, v215, v184
	v_add_f32_e32 v200, v216, v185
	v_fma_f32 v201, v134, v182, v217
	v_fma_f32 v202, v134, v187, v195
	v_fma_f32 v224, v134, v199, v188
	v_fma_f32 v249, v134, v192, v200
	v_fma_f32 v250, v135, v245, v201
	v_fma_f32 v251, v135, v246, v202
	v_fma_f32 v252, v135, v247, v224
	v_fma_f32 v255, v135, v228, v249
	v_lshlrev_b32_e32 v179, 16, v50
	v_and_b32_e32 v180, s100, v50
	v_lshlrev_b32_e32 v181, 16, v51
	v_and_b32_e32 v182, s100, v51
	v_add_f32_e32 v187, v179, v173
	v_add_f32_e32 v199, v180, v214
	v_add_f32_e32 v192, v181, v215
	v_add_f32_e32 v245, v182, v216
	v_fma_f32 v246, v134, v186, v187
	v_fma_f32 v247, v134, v191, v199
	v_fma_f32 v228, v134, v244, v192
	v_fma_f32 v204, v134, v196, v245
	v_fma_f32 v205, v135, v189, v246
	v_fma_f32 v206, v135, v190, v247
	v_fma_f32 v175, v135, v203, v228
	v_fma_f32 v178, v135, v232, v204
	v_lshlrev_b32_e32 v183, 16, v54
	v_and_b32_e32 v184, s100, v54
	v_lshlrev_b32_e32 v185, 16, v55
	v_and_b32_e32 v186, s100, v55
	v_add_f32_e32 v191, v183, v179
	v_add_f32_e32 v244, v184, v180
	v_add_f32_e32 v196, v185, v181
	v_add_f32_e32 v189, v186, v182
	v_fma_f32 v190, v134, v217, v191
	v_fma_f32 v203, v134, v195, v244
	v_fma_f32 v232, v134, v188, v196
	v_fma_f32 v208, v134, v200, v189
	v_fma_f32 v209, v135, v193, v190
	v_fma_f32 v210, v135, v194, v203
	v_fma_f32 v0, v135, v207, v232
	v_fma_f32 v173, v135, v236, v208
	v_lshlrev_b32_e32 v214, 16, v58
	v_and_b32_e32 v215, s100, v58
	v_lshlrev_b32_e32 v216, 16, v59
	v_and_b32_e32 v217, s100, v59
	v_add_f32_e32 v195, v214, v183
	v_add_f32_e32 v188, v215, v184
	v_add_f32_e32 v200, v216, v185
	v_add_f32_e32 v193, v217, v186
	v_fma_f32 v194, v134, v187, v195
	v_fma_f32 v207, v134, v199, v188
	v_fma_f32 v236, v134, v192, v200
	v_fma_f32 v221, v134, v245, v193
	v_fma_f32 v222, v135, v197, v194
	v_fma_f32 v223, v135, v198, v207
	v_fma_f32 v253, v135, v211, v236
	v_fma_f32 v179, v135, v240, v221
	v_lshlrev_b32_e32 v180, 16, v62
; __device__ __forceinline__ unsigned pk2(float lo, float hi) { return pg8::cvt_pk_bf16(lo, hi); }
; __global__ void __launch_bounds__(NTHR, 2) hybrid_fwd(Args args) {
;     ...
;         for (int i = 0; i < nr; ++i) { const int t = t_b + i;
;             const int sp = t & 2047, cnt = (sp + 1) < w ? (sp + 1) : w;
;             u32x4 qv[16];
; #pragma unroll
;             for (int j = 0; j < 16; ++j) qv[j] = qn[j];
;             if (i + 1 < nr) { const int t1 = t + 1, sp1 = t1 & 2047, c1_ = (sp1 + 1) < w ? (sp1 + 1) : w;
; #pragma unroll
;                 for (int j = 0; j < 16; ++j) qn[j] = *(const u32x4*)(UB + (size_t)(j < c1_ ? t1 - j : t1) * 512 + lane * 8); }
;             float a[8];
; #pragma unroll
;             for (int e = 0; e < 8; ++e) a[e] = 0.f;
;             const u32x4 u0 = qv[0];
; #pragma unroll
;             for (int j = 0; j < 16; ++j) { const float mk = j < cnt ? 1.0f : 0.0f; const u32x4 q = qv[j];
;                 a[0] += mk * bflo(q.x); a[1] += mk * bfhi(q.x); a[2] += mk * bflo(q.y); a[3] += mk * bfhi(q.y); a[4] += mk * bflo(q.z); a[5] += mk * bfhi(q.z); a[6] += mk * bflo(q.w); a[7] += mk * bfhi(q.w); }
;             const float ic = 1.0f / (float)cnt;
;             u32x4 o; o.x = pk2(a[0] * ic - bflo(u0.x), a[1] * ic - bfhi(u0.x)); o.y = pk2(a[2] * ic - bflo(u0.y), a[3] * ic - bfhi(u0.y));
;             o.z = pk2(a[4] * ic - bflo(u0.z), a[5] * ic - bfhi(u0.z)); o.w = pk2(a[6] * ic - bflo(u0.w), a[7] * ic - bfhi(u0.w));
;             *(u32x4*)(AD + (size_t)t * 1024 + lane * 8) = o; }
	v_and_b32_e32 v181, s100, v62
	v_lshlrev_b32_e32 v182, 16, v63
	v_and_b32_e32 v187, s100, v63
	v_add_f32_e32 v199, v180, v214
	v_add_f32_e32 v192, v181, v215
	v_add_f32_e32 v245, v182, v216
	v_add_f32_e32 v197, v187, v217
	v_fma_f32 v198, v134, v191, v199
	v_fma_f32 v211, v134, v244, v192
	v_fma_f32 v240, v134, v196, v245
	v_fma_f32 v225, v134, v189, v197
	v_fma_f32 v226, v135, v201, v198
	v_fma_f32 v227, v135, v202, v211
	v_fma_f32 v176, v135, v224, v240
	v_fma_f32 v183, v135, v249, v225
	v_lshlrev_b32_e32 v184, 16, v66
	v_and_b32_e32 v185, s100, v66
	v_lshlrev_b32_e32 v186, 16, v67
	v_and_b32_e32 v191, s100, v67
	v_add_f32_e32 v244, v184, v180
	v_add_f32_e32 v196, v185, v181
	v_add_f32_e32 v189, v186, v182
	v_add_f32_e32 v201, v191, v187
	v_fma_f32 v202, v134, v195, v244
	v_fma_f32 v224, v134, v188, v196
	v_fma_f32 v249, v134, v200, v189
	v_fma_f32 v229, v134, v193, v201
	v_fma_f32 v230, v135, v246, v202
	v_fma_f32 v231, v135, v247, v224
	v_fma_f32 v1, v135, v228, v249
	v_fma_f32 v214, v135, v204, v229
	v_lshlrev_b32_e32 v215, 16, v70
	v_and_b32_e32 v216, s100, v70
	v_lshlrev_b32_e32 v217, 16, v71
	v_and_b32_e32 v195, s100, v71
	v_add_f32_e32 v188, v215, v184
	v_add_f32_e32 v200, v216, v185
	v_add_f32_e32 v193, v217, v186
	v_add_f32_e32 v246, v195, v191
	v_fma_f32 v247, v134, v199, v188
	v_fma_f32 v228, v134, v192, v200
	v_fma_f32 v204, v134, v245, v193
	v_fma_f32 v233, v134, v197, v246
	v_fma_f32 v234, v135, v190, v247
	v_fma_f32 v235, v135, v203, v228
	v_fma_f32 v254, v135, v232, v204
	v_fma_f32 v180, v135, v208, v233
	v_fma_f32 v181, v136, v237, v234
	v_fma_f32 v182, v136, v238, v235
	v_fma_f32 v187, v136, v239, v254
	v_fma_f32 v199, v136, v177, v180
	s_add_i32 s101, s99, 1
	v_min_u32_e32 v192, s101, v137
	v_cvt_f32_u32_e32 v192, v192
	v_rcp_f32_e32 v192, v192
	s_nop 0
	v_fma_f32 v181, v181, v192, -v215
	v_fma_f32 v182, v182, v192, -v216
	v_fma_f32 v187, v187, v192, -v217
	v_fma_f32 v199, v199, v192, -v195
	v_cvt_pk_bf16_f32 v70, v181, v182
	v_cvt_pk_bf16_f32 v71, v187, v199
	global_store_dwordx4 v[138:139], v[68:71], off
	v_lshlrev_b32_e32 v245, 16, v74
	v_and_b32_e32 v197, s100, v74
	v_lshlrev_b32_e32 v190, 16, v75
	v_and_b32_e32 v203, s100, v75
	v_add_f32_e32 v232, v245, v215
	v_add_f32_e32 v208, v197, v216
	v_add_f32_e32 v237, v190, v217
	v_add_f32_e32 v238, v203, v195
	v_fma_f32 v239, v134, v244, v232
	v_fma_f32 v177, v134, v196, v208
	v_fma_f32 v181, v134, v189, v237
	v_fma_f32 v182, v134, v201, v238
	v_fma_f32 v187, v135, v194, v239
	v_fma_f32 v199, v135, v207, v177
	v_fma_f32 v192, v135, v236, v181
	v_fma_f32 v184, v135, v221, v182
	v_fma_f32 v185, v136, v241, v187
	v_fma_f32 v186, v136, v242, v199
	v_fma_f32 v191, v136, v243, v192
	v_fma_f32 v244, v136, v172, v184
	s_add_i32 s101, s99, 2
	v_min_u32_e32 v196, s101, v137
	v_cvt_f32_u32_e32 v196, v196
	v_rcp_f32_e32 v196, v196
	s_nop 0
	v_fma_f32 v185, v185, v196, -v245
	v_fma_f32 v186, v186, v196, -v197
	v_fma_f32 v191, v191, v196, -v190
	v_fma_f32 v244, v244, v196, -v203
	v_cvt_pk_bf16_f32 v74, v185, v186
	v_cvt_pk_bf16_f32 v75, v191, v244
	global_store_dwordx4 v[138:139], v[72:75], off offset:2048
	v_lshl_add_u64 v[138:139], v[138:139], 0, s[26:27]
	v_lshlrev_b32_e32 v189, 16, v78
	v_and_b32_e32 v201, s100, v78
	v_lshlrev_b32_e32 v194, 16, v79
	v_and_b32_e32 v207, s100, v79
	v_add_f32_e32 v236, v189, v245
	v_add_f32_e32 v221, v201, v197
	v_add_f32_e32 v241, v194, v190
	v_add_f32_e32 v242, v207, v203
	v_fma_f32 v243, v134, v188, v236
	v_fma_f32 v172, v134, v200, v221
	v_fma_f32 v185, v134, v193, v241
	v_fma_f32 v186, v134, v246, v242
	v_fma_f32 v191, v135, v198, v243
	v_fma_f32 v244, v135, v211, v172
	v_fma_f32 v196, v135, v240, v185
	v_fma_f32 v215, v135, v225, v186
	v_fma_f32 v216, v136, v250, v191
	v_fma_f32 v217, v136, v251, v244
	v_fma_f32 v195, v136, v252, v196
	v_fma_f32 v188, v136, v255, v215
	s_add_i32 s101, s99, 3
	v_min_u32_e32 v200, s101, v137
	v_cvt_f32_u32_e32 v200, v200
	v_rcp_f32_e32 v200, v200
	s_nop 0
	v_fma_f32 v216, v216, v200, -v189
	v_fma_f32 v217, v217, v200, -v201
	v_fma_f32 v195, v195, v200, -v194
	v_fma_f32 v188, v188, v200, -v207
	v_cvt_pk_bf16_f32 v78, v216, v217
	v_cvt_pk_bf16_f32 v79, v195, v188
	global_store_dwordx4 v[138:139], v[76:79], off
	v_lshlrev_b32_e32 v193, 16, v82
	v_and_b32_e32 v246, s100, v82
	v_lshlrev_b32_e32 v198, 16, v83
	v_and_b32_e32 v211, s100, v83
	v_add_f32_e32 v240, v193, v189
	v_add_f32_e32 v225, v246, v201
	v_add_f32_e32 v250, v198, v194
	v_add_f32_e32 v251, v211, v207
	v_fma_f32 v252, v134, v232, v240
	v_fma_f32 v255, v134, v208, v225
	v_fma_f32 v216, v134, v237, v250
	v_fma_f32 v217, v134, v238, v251
	v_fma_f32 v195, v135, v202, v252
	v_fma_f32 v188, v135, v224, v255
	v_fma_f32 v200, v135, v249, v216
	v_fma_f32 v245, v135, v229, v217
	v_fma_f32 v197, v136, v205, v195
	v_fma_f32 v190, v136, v206, v188
	v_fma_f32 v203, v136, v175, v200
	v_fma_f32 v232, v136, v178, v245
	s_add_i32 s101, s99, 4
	v_min_u32_e32 v208, s101, v137
	v_cvt_f32_u32_e32 v208, v208
	v_rcp_f32_e32 v208, v208
	s_nop 0
	v_fma_f32 v197, v197, v208, -v193
	v_fma_f32 v190, v190, v208, -v246
	v_fma_f32 v203, v203, v208, -v198
	v_fma_f32 v232, v232, v208, -v211
	v_cvt_pk_bf16_f32 v82, v197, v190
	v_cvt_pk_bf16_f32 v83, v203, v232
	global_store_dwordx4 v[138:139], v[80:83], off offset:2048
	v_lshl_add_u64 v[138:139], v[138:139], 0, s[26:27]
	v_lshlrev_b32_e32 v237, 16, v86
	v_and_b32_e32 v238, s100, v86
	v_lshlrev_b32_e32 v202, 16, v87
	v_and_b32_e32 v224, s100, v87
	v_add_f32_e32 v249, v237, v193
	v_add_f32_e32 v229, v238, v246
	v_add_f32_e32 v205, v202, v198
	v_add_f32_e32 v206, v224, v211
	v_fma_f32 v175, v134, v236, v249
	v_fma_f32 v178, v134, v221, v229
; __device__ __forceinline__ unsigned pk2(float lo, float hi) { return pg8::cvt_pk_bf16(lo, hi); }
; __global__ void __launch_bounds__(NTHR, 2) hybrid_fwd(Args args) {
;     ...
;         for (int i = 0; i < nr; ++i) { const int t = t_b + i;
;             const int sp = t & 2047, cnt = (sp + 1) < w ? (sp + 1) : w;
;             u32x4 qv[16];
; #pragma unroll
;             for (int j = 0; j < 16; ++j) qv[j] = qn[j];
;             if (i + 1 < nr) { const int t1 = t + 1, sp1 = t1 & 2047, c1_ = (sp1 + 1) < w ? (sp1 + 1) : w;
; #pragma unroll
;                 for (int j = 0; j < 16; ++j) qn[j] = *(const u32x4*)(UB + (size_t)(j < c1_ ? t1 - j : t1) * 512 + lane * 8); }
;             float a[8];
; #pragma unroll
;             for (int e = 0; e < 8; ++e) a[e] = 0.f;
;             const u32x4 u0 = qv[0];
; #pragma unroll
;             for (int j = 0; j < 16; ++j) { const float mk = j < cnt ? 1.0f : 0.0f; const u32x4 q = qv[j];
;                 a[0] += mk * bflo(q.x); a[1] += mk * bfhi(q.x); a[2] += mk * bflo(q.y); a[3] += mk * bfhi(q.y); a[4] += mk * bflo(q.z); a[5] += mk * bfhi(q.z); a[6] += mk * bflo(q.w); a[7] += mk * bfhi(q.w); }
;             const float ic = 1.0f / (float)cnt;
;             u32x4 o; o.x = pk2(a[0] * ic - bflo(u0.x), a[1] * ic - bfhi(u0.x)); o.y = pk2(a[2] * ic - bflo(u0.y), a[3] * ic - bfhi(u0.y));
;             o.z = pk2(a[4] * ic - bflo(u0.z), a[5] * ic - bfhi(u0.z)); o.w = pk2(a[6] * ic - bflo(u0.w), a[7] * ic - bfhi(u0.w));
;             *(u32x4*)(AD + (size_t)t * 1024 + lane * 8) = o; }
	v_fma_f32 v197, v134, v241, v205
	v_fma_f32 v190, v134, v242, v206
	v_fma_f32 v203, v135, v247, v175
	v_fma_f32 v232, v135, v228, v178
	v_fma_f32 v208, v135, v204, v197
	v_fma_f32 v189, v135, v233, v190
	v_fma_f32 v201, v136, v209, v203
	v_fma_f32 v194, v136, v210, v232
	v_fma_f32 v207, v136, v0, v208
	v_fma_f32 v236, v136, v173, v189
	s_add_i32 s101, s99, 5
	v_min_u32_e32 v221, s101, v137
	v_cvt_f32_u32_e32 v221, v221
	v_rcp_f32_e32 v221, v221
	s_nop 0
	v_fma_f32 v201, v201, v221, -v237
	v_fma_f32 v194, v194, v221, -v238
	v_fma_f32 v207, v207, v221, -v202
	v_fma_f32 v236, v236, v221, -v224
	v_cvt_pk_bf16_f32 v86, v201, v194
	v_cvt_pk_bf16_f32 v87, v207, v236
	global_store_dwordx4 v[138:139], v[84:87], off
	v_lshlrev_b32_e32 v241, 16, v90
	v_and_b32_e32 v242, s100, v90
	v_lshlrev_b32_e32 v247, 16, v91
	v_and_b32_e32 v228, s100, v91
	v_add_f32_e32 v204, v241, v237
	v_add_f32_e32 v233, v242, v238
	v_add_f32_e32 v209, v247, v202
	v_add_f32_e32 v210, v228, v224
	v_fma_f32 v0, v134, v240, v204
	v_fma_f32 v173, v134, v225, v233
	v_fma_f32 v201, v134, v250, v209
	v_fma_f32 v194, v134, v251, v210
	v_fma_f32 v207, v135, v239, v0
	v_fma_f32 v236, v135, v177, v173
	v_fma_f32 v221, v135, v181, v201
	v_fma_f32 v193, v135, v182, v194
	v_fma_f32 v246, v136, v222, v207
	v_fma_f32 v198, v136, v223, v236
	v_fma_f32 v211, v136, v253, v221
	v_fma_f32 v240, v136, v179, v193
	s_add_i32 s101, s99, 6
	v_min_u32_e32 v225, s101, v137
	v_cvt_f32_u32_e32 v225, v225
	v_rcp_f32_e32 v225, v225
	s_nop 0
	v_fma_f32 v246, v246, v225, -v241
	v_fma_f32 v198, v198, v225, -v242
	v_fma_f32 v211, v211, v225, -v247
	v_fma_f32 v240, v240, v225, -v228
	v_cvt_pk_bf16_f32 v90, v246, v198
	v_cvt_pk_bf16_f32 v91, v211, v240
	global_store_dwordx4 v[138:139], v[88:91], off offset:2048
	v_lshl_add_u64 v[138:139], v[138:139], 0, s[26:27]
	v_lshlrev_b32_e32 v250, 16, v94
	v_and_b32_e32 v251, s100, v94
	v_lshlrev_b32_e32 v239, 16, v95
	v_and_b32_e32 v177, s100, v95
	v_add_f32_e32 v181, v250, v241
	v_add_f32_e32 v182, v251, v242
	v_add_f32_e32 v222, v239, v247
	v_add_f32_e32 v223, v177, v228
	v_fma_f32 v253, v134, v249, v181
	v_fma_f32 v179, v134, v229, v182
	v_fma_f32 v246, v134, v205, v222
	v_fma_f32 v198, v134, v206, v223
	v_fma_f32 v211, v135, v243, v253
	v_fma_f32 v240, v135, v172, v179
	v_fma_f32 v225, v135, v185, v246
	v_fma_f32 v237, v135, v186, v198
	v_fma_f32 v238, v136, v226, v211
	v_fma_f32 v202, v136, v227, v240
	v_fma_f32 v224, v136, v176, v225
	v_fma_f32 v249, v136, v183, v237
	s_add_i32 s101, s99, 7
	v_min_u32_e32 v229, s101, v137
	v_cvt_f32_u32_e32 v229, v229
	v_rcp_f32_e32 v229, v229
	s_nop 0
	v_fma_f32 v238, v238, v229, -v250
	v_fma_f32 v202, v202, v229, -v251
	v_fma_f32 v224, v224, v229, -v239
	v_fma_f32 v249, v249, v229, -v177
	v_cvt_pk_bf16_f32 v94, v238, v202
	v_cvt_pk_bf16_f32 v95, v224, v249
	global_store_dwordx4 v[138:139], v[92:95], off
	v_lshlrev_b32_e32 v205, 16, v98
	v_and_b32_e32 v206, s100, v98
	v_lshlrev_b32_e32 v243, 16, v99
	v_and_b32_e32 v172, s100, v99
	v_add_f32_e32 v185, v205, v250
	v_add_f32_e32 v186, v206, v251
	v_add_f32_e32 v226, v243, v239
	v_add_f32_e32 v227, v172, v177
	v_fma_f32 v176, v134, v204, v185
	v_fma_f32 v183, v134, v233, v186
	v_fma_f32 v238, v134, v209, v226
	v_fma_f32 v202, v134, v210, v227
	v_fma_f32 v224, v135, v252, v176
	v_fma_f32 v249, v135, v255, v183
	v_fma_f32 v229, v135, v216, v238
	v_fma_f32 v241, v135, v217, v202
	v_fma_f32 v242, v136, v230, v224
	v_fma_f32 v247, v136, v231, v249
	v_fma_f32 v228, v136, v1, v229
	v_fma_f32 v204, v136, v214, v241
	s_add_i32 s101, s99, 8
	v_min_u32_e32 v233, s101, v137
	v_cvt_f32_u32_e32 v233, v233
	v_rcp_f32_e32 v233, v233
	s_nop 0
	v_fma_f32 v242, v242, v233, -v205
	v_fma_f32 v247, v247, v233, -v206
	v_fma_f32 v228, v228, v233, -v243
	v_fma_f32 v204, v204, v233, -v172
	v_cvt_pk_bf16_f32 v98, v242, v247
	v_cvt_pk_bf16_f32 v99, v228, v204
	global_store_dwordx4 v[138:139], v[96:99], off offset:2048
	v_lshl_add_u64 v[138:139], v[138:139], 0, s[26:27]
	v_lshlrev_b32_e32 v209, 16, v102
	v_and_b32_e32 v210, s100, v102
	v_lshlrev_b32_e32 v252, 16, v103
	v_and_b32_e32 v255, s100, v103
	v_add_f32_e32 v216, v209, v205
	v_add_f32_e32 v217, v210, v206
	v_add_f32_e32 v230, v252, v243
	v_add_f32_e32 v231, v255, v172
	v_fma_f32 v1, v134, v181, v216
	v_fma_f32 v214, v134, v182, v217
	v_fma_f32 v242, v134, v222, v230
	v_fma_f32 v247, v134, v223, v231
	v_fma_f32 v228, v135, v175, v1
	v_fma_f32 v204, v135, v178, v214
	v_fma_f32 v233, v135, v197, v242
	v_fma_f32 v250, v135, v190, v247
	v_fma_f32 v251, v136, v234, v228
	v_fma_f32 v239, v136, v235, v204
	v_fma_f32 v177, v136, v254, v233
	v_fma_f32 v181, v136, v180, v250
	s_add_i32 s101, s99, 9
	v_min_u32_e32 v182, s101, v137
	v_cvt_f32_u32_e32 v182, v182
	v_rcp_f32_e32 v182, v182
	s_nop 0
	v_fma_f32 v251, v251, v182, -v209
	v_fma_f32 v239, v239, v182, -v210
	v_fma_f32 v177, v177, v182, -v252
	v_fma_f32 v181, v181, v182, -v255
	v_cvt_pk_bf16_f32 v102, v251, v239
	v_cvt_pk_bf16_f32 v103, v177, v181
	global_store_dwordx4 v[138:139], v[100:103], off
	v_lshlrev_b32_e32 v222, 16, v106
	v_and_b32_e32 v223, s100, v106
	v_lshlrev_b32_e32 v175, 16, v107
	v_and_b32_e32 v178, s100, v107
	v_add_f32_e32 v197, v222, v209
	v_add_f32_e32 v190, v223, v210
	v_add_f32_e32 v234, v175, v252
	v_add_f32_e32 v235, v178, v255
	v_fma_f32 v254, v134, v185, v197
	v_fma_f32 v180, v134, v186, v190
	v_fma_f32 v251, v134, v226, v234
	v_fma_f32 v239, v134, v227, v235
	v_fma_f32 v177, v135, v0, v254
	v_fma_f32 v181, v135, v173, v180
	v_fma_f32 v182, v135, v201, v251
	v_fma_f32 v205, v135, v194, v239
	v_fma_f32 v206, v136, v187, v177
	v_fma_f32 v243, v136, v199, v181
	v_fma_f32 v172, v136, v192, v182
; __device__ __forceinline__ unsigned pk2(float lo, float hi) { return pg8::cvt_pk_bf16(lo, hi); }
; __global__ void __launch_bounds__(NTHR, 2) hybrid_fwd(Args args) {
;     ...
;         for (int i = 0; i < nr; ++i) { const int t = t_b + i;
;             const int sp = t & 2047, cnt = (sp + 1) < w ? (sp + 1) : w;
;             u32x4 qv[16];
; #pragma unroll
;             for (int j = 0; j < 16; ++j) qv[j] = qn[j];
;             if (i + 1 < nr) { const int t1 = t + 1, sp1 = t1 & 2047, c1_ = (sp1 + 1) < w ? (sp1 + 1) : w;
; #pragma unroll
;                 for (int j = 0; j < 16; ++j) qn[j] = *(const u32x4*)(UB + (size_t)(j < c1_ ? t1 - j : t1) * 512 + lane * 8); }
;             float a[8];
; #pragma unroll
;             for (int e = 0; e < 8; ++e) a[e] = 0.f;
;             const u32x4 u0 = qv[0];
; #pragma unroll
;             for (int j = 0; j < 16; ++j) { const float mk = j < cnt ? 1.0f : 0.0f; const u32x4 q = qv[j];
;                 a[0] += mk * bflo(q.x); a[1] += mk * bfhi(q.x); a[2] += mk * bflo(q.y); a[3] += mk * bfhi(q.y); a[4] += mk * bflo(q.z); a[5] += mk * bfhi(q.z); a[6] += mk * bflo(q.w); a[7] += mk * bfhi(q.w); }
;             const float ic = 1.0f / (float)cnt;
;             u32x4 o; o.x = pk2(a[0] * ic - bflo(u0.x), a[1] * ic - bfhi(u0.x)); o.y = pk2(a[2] * ic - bflo(u0.y), a[3] * ic - bfhi(u0.y));
;             o.z = pk2(a[4] * ic - bflo(u0.z), a[5] * ic - bfhi(u0.z)); o.w = pk2(a[6] * ic - bflo(u0.w), a[7] * ic - bfhi(u0.w));
;             *(u32x4*)(AD + (size_t)t * 1024 + lane * 8) = o; }
	v_fma_f32 v185, v136, v184, v205
	s_add_i32 s101, s99, 10
	v_min_u32_e32 v186, s101, v137
	v_cvt_f32_u32_e32 v186, v186
	v_rcp_f32_e32 v186, v186
	s_nop 0
	v_fma_f32 v206, v206, v186, -v222
	v_fma_f32 v243, v243, v186, -v223
	v_fma_f32 v172, v172, v186, -v175
	v_fma_f32 v185, v185, v186, -v178
	v_cvt_pk_bf16_f32 v106, v206, v243
	v_cvt_pk_bf16_f32 v107, v172, v185
	global_store_dwordx4 v[138:139], v[104:107], off offset:2048
	v_lshl_add_u64 v[138:139], v[138:139], 0, s[26:27]
	v_lshlrev_b32_e32 v226, 16, v110
	v_and_b32_e32 v227, s100, v110
	v_lshlrev_b32_e32 v0, 16, v111
	v_and_b32_e32 v173, s100, v111
	v_add_f32_e32 v201, v226, v222
	v_add_f32_e32 v194, v227, v223
	v_add_f32_e32 v187, v0, v175
	v_add_f32_e32 v199, v173, v178
	v_fma_f32 v192, v134, v216, v201
	v_fma_f32 v184, v134, v217, v194
	v_fma_f32 v206, v134, v230, v187
	v_fma_f32 v243, v134, v231, v199
	v_fma_f32 v172, v135, v253, v192
	v_fma_f32 v185, v135, v179, v184
	v_fma_f32 v186, v135, v246, v206
	v_fma_f32 v209, v135, v198, v243
	v_fma_f32 v210, v136, v191, v172
	v_fma_f32 v252, v136, v244, v185
	v_fma_f32 v255, v136, v196, v186
	v_fma_f32 v216, v136, v215, v209
	s_add_i32 s101, s99, 11
	v_min_u32_e32 v217, s101, v137
	v_cvt_f32_u32_e32 v217, v217
	v_rcp_f32_e32 v217, v217
	s_nop 0
	v_fma_f32 v210, v210, v217, -v226
	v_fma_f32 v252, v252, v217, -v227
	v_fma_f32 v255, v255, v217, -v0
	v_fma_f32 v216, v216, v217, -v173
	v_cvt_pk_bf16_f32 v110, v210, v252
	v_cvt_pk_bf16_f32 v111, v255, v216
	global_store_dwordx4 v[138:139], v[108:111], off
	v_lshlrev_b32_e32 v230, 16, v114
	v_and_b32_e32 v231, s100, v114
	v_lshlrev_b32_e32 v253, 16, v115
	v_and_b32_e32 v179, s100, v115
	v_add_f32_e32 v246, v230, v226
	v_add_f32_e32 v198, v231, v227
	v_add_f32_e32 v191, v253, v0
	v_add_f32_e32 v244, v179, v173
	v_fma_f32 v196, v134, v197, v246
	v_fma_f32 v215, v134, v190, v198
	v_fma_f32 v210, v134, v234, v191
	v_fma_f32 v252, v134, v235, v244
	v_fma_f32 v255, v135, v176, v196
	v_fma_f32 v216, v135, v183, v215
	v_fma_f32 v217, v135, v238, v210
	v_fma_f32 v222, v135, v202, v252
	v_fma_f32 v223, v136, v195, v255
	v_fma_f32 v175, v136, v188, v216
	v_fma_f32 v178, v136, v200, v217
	v_fma_f32 v197, v136, v245, v222
	s_add_i32 s101, s99, 12
	v_min_u32_e32 v190, s101, v137
	v_cvt_f32_u32_e32 v190, v190
	v_rcp_f32_e32 v190, v190
	s_nop 0
	v_fma_f32 v223, v223, v190, -v230
	v_fma_f32 v175, v175, v190, -v231
	v_fma_f32 v178, v178, v190, -v253
	v_fma_f32 v197, v197, v190, -v179
	v_cvt_pk_bf16_f32 v114, v223, v175
	v_cvt_pk_bf16_f32 v115, v178, v197
	global_store_dwordx4 v[138:139], v[112:115], off offset:2048
	v_lshl_add_u64 v[138:139], v[138:139], 0, s[26:27]
	v_lshlrev_b32_e32 v234, 16, v118
	v_and_b32_e32 v235, s100, v118
	v_lshlrev_b32_e32 v176, 16, v119
	v_and_b32_e32 v183, s100, v119
	v_add_f32_e32 v238, v234, v230
	v_add_f32_e32 v202, v235, v231
	v_add_f32_e32 v195, v176, v253
	v_add_f32_e32 v188, v183, v179
	v_fma_f32 v200, v134, v201, v238
	v_fma_f32 v245, v134, v194, v202
	v_fma_f32 v223, v134, v187, v195
	v_fma_f32 v175, v134, v199, v188
	v_fma_f32 v178, v135, v1, v200
	v_fma_f32 v197, v135, v214, v245
	v_fma_f32 v190, v135, v242, v223
	v_fma_f32 v226, v135, v247, v175
	v_fma_f32 v227, v136, v203, v178
	v_fma_f32 v0, v136, v232, v197
	v_fma_f32 v173, v136, v208, v190
	v_fma_f32 v201, v136, v189, v226
	s_add_i32 s101, s99, 13
	v_min_u32_e32 v194, s101, v137
	v_cvt_f32_u32_e32 v194, v194
	v_rcp_f32_e32 v194, v194
	s_nop 0
	v_fma_f32 v227, v227, v194, -v234
	v_fma_f32 v0, v0, v194, -v235
	v_fma_f32 v173, v173, v194, -v176
	v_fma_f32 v201, v201, v194, -v183
	v_cvt_pk_bf16_f32 v118, v227, v0
	v_cvt_pk_bf16_f32 v119, v173, v201
	global_store_dwordx4 v[138:139], v[116:119], off
	v_lshlrev_b32_e32 v187, 16, v122
	v_and_b32_e32 v199, s100, v122
	v_lshlrev_b32_e32 v1, 16, v123
	v_and_b32_e32 v214, s100, v123
	v_add_f32_e32 v242, v187, v234
	v_add_f32_e32 v247, v199, v235
	v_add_f32_e32 v203, v1, v176
	v_add_f32_e32 v232, v214, v183
	v_fma_f32 v208, v134, v246, v242
	v_fma_f32 v189, v134, v198, v247
	v_fma_f32 v227, v134, v191, v203
	v_fma_f32 v0, v134, v244, v232
	v_fma_f32 v173, v135, v254, v208
	v_fma_f32 v201, v135, v180, v189
	v_fma_f32 v194, v135, v251, v227
	v_fma_f32 v230, v135, v239, v0
	v_fma_f32 v231, v136, v207, v173
	v_fma_f32 v253, v136, v236, v201
	v_fma_f32 v179, v136, v221, v194
	v_fma_f32 v246, v136, v193, v230
	s_add_i32 s101, s99, 14
	v_min_u32_e32 v198, s101, v137
	v_cvt_f32_u32_e32 v198, v198
	v_rcp_f32_e32 v198, v198
	s_nop 0
	v_fma_f32 v231, v231, v198, -v187
	v_fma_f32 v253, v253, v198, -v199
	v_fma_f32 v179, v179, v198, -v1
	v_fma_f32 v246, v246, v198, -v214
	v_cvt_pk_bf16_f32 v122, v231, v253
	v_cvt_pk_bf16_f32 v123, v179, v246
	global_store_dwordx4 v[138:139], v[120:123], off offset:2048
	v_lshl_add_u64 v[138:139], v[138:139], 0, s[26:27]
	v_lshlrev_b32_e32 v191, 16, v126
	v_and_b32_e32 v244, s100, v126
	v_lshlrev_b32_e32 v254, 16, v127
	v_and_b32_e32 v180, s100, v127
	v_add_f32_e32 v251, v191, v187
	v_add_f32_e32 v239, v244, v199
	v_add_f32_e32 v207, v254, v1
	v_add_f32_e32 v236, v180, v214
	v_fma_f32 v221, v134, v238, v251
	v_fma_f32 v193, v134, v202, v239
	v_fma_f32 v231, v134, v195, v207
	v_fma_f32 v253, v134, v188, v236
	v_fma_f32 v179, v135, v192, v221
	v_fma_f32 v246, v135, v184, v193
	v_fma_f32 v198, v135, v206, v231
	v_fma_f32 v234, v135, v243, v253
	v_fma_f32 v235, v136, v211, v179
	v_fma_f32 v176, v136, v240, v246
	v_fma_f32 v183, v136, v225, v198
	v_fma_f32 v238, v136, v237, v234
	s_add_i32 s101, s99, 15
	v_min_u32_e32 v202, s101, v137
	v_cvt_f32_u32_e32 v202, v202
	v_rcp_f32_e32 v202, v202
	s_nop 0
	v_fma_f32 v235, v235, v202, -v191
	v_fma_f32 v176, v176, v202, -v244
	v_fma_f32 v183, v183, v202, -v254
	v_fma_f32 v238, v238, v202, -v180
	v_cvt_pk_bf16_f32 v126, v235, v176
	v_cvt_pk_bf16_f32 v127, v183, v238
	global_store_dwordx4 v[138:139], v[124:127], off
	v_lshlrev_b32_e32 v195, 16, v130
	v_and_b32_e32 v188, s100, v130
	v_lshlrev_b32_e32 v192, 16, v131
	v_and_b32_e32 v184, s100, v131
	v_add_f32_e32 v206, v195, v191
	v_add_f32_e32 v243, v188, v244
	v_add_f32_e32 v211, v192, v254
	v_add_f32_e32 v240, v184, v180
	v_fma_f32 v225, v134, v242, v206
	v_fma_f32 v237, v134, v247, v243
	v_fma_f32 v235, v134, v203, v211
	v_fma_f32 v176, v134, v232, v240
	v_fma_f32 v183, v135, v196, v225
	v_fma_f32 v238, v135, v215, v237
	v_fma_f32 v202, v135, v210, v235
	v_fma_f32 v187, v135, v252, v176
	v_fma_f32 v199, v136, v224, v183
	v_fma_f32 v1, v136, v249, v238
	v_fma_f32 v214, v136, v229, v202
	v_fma_f32 v242, v136, v241, v187
	s_add_i32 s101, s99, 16
	v_min_u32_e32 v247, s101, v137
	v_cvt_f32_u32_e32 v247, v247
	v_rcp_f32_e32 v247, v247
	s_nop 0
	v_fma_f32 v199, v199, v247, -v195
	v_fma_f32 v1, v1, v247, -v188
	v_fma_f32 v214, v214, v247, -v192
	v_fma_f32 v242, v242, v247, -v184
	v_cvt_pk_bf16_f32 v130, v199, v1
	v_cvt_pk_bf16_f32 v131, v214, v242
	global_store_dwordx4 v[138:139], v[128:131], off offset:2048
	s_branch .LBB0_377
